# non-temporal (nt) cache hints on the read-once residual loads and f32 out stores of the P3/P10/P13 EpiResid epilogues
# speedup vs baseline: 1.0047x; 1.0047x over previous
; DEV u32x4 pack8v(const f32x4 a, const f32x4 b) { u32x4 w; w.x = cvt_pk_bf16(a[0], a[1]); w.y = cvt_pk_bf16(a[2], a[3]); w.z = cvt_pk_bf16(b[0], b[1]); w.w = cvt_pk_bf16(b[2], b[3]); return w; }
;     DEV void operator()(const f32x4 (&acc)[2][2][4][2], const Unit& u, int wr, int wc, int fr, int fq) const {
;     ...
;         const bool lat = u.pm < MLAT / 256; const int b = lat ? (u.pm >> 4) : 16;
;         const float* res = lat ? res_lat : res_ctx; float* out = lat ? out_lat : out_ctx;
;         const int grow0 = u.pm * 256 + wr * 64 + fr, row0 = (lat ? grow0 : grow0 - MLAT), col0 = u.pn * 256 + wc * 32 + (PERM ? 8 : 4) * fq;
;         float ss[8];
; #pragma unroll
;         for (int i = 0; i < 8; ++i) ss[i] = 0.f;
; #pragma unroll
;         for (int bj = 0; bj < 2; ++bj) {
;             f32x4 gv[2], gs[2];
; #pragma unroll
;             for (int n = 0; n < 2; ++n) { gv[n] = *(const f32x4*)(mod + (size_t)b * NMOD + gate_i * D + col0 + bj * 128 + NS * n) * coef;
;                 if (has_xn) gs[n] = *(const f32x4*)(g + col0 + bj * 128 + 4 * n) * (*(const f32x4*)(mod + (size_t)b * NMOD + scale_i * D + col0 + bj * 128 + 4 * n) + 1.f); }
; #pragma unroll
;             for (int ai = 0; ai < 2; ++ai)
; #pragma unroll
;                 for (int m = 0; m < 4; ++m) {
;                     const size_t p = (size_t)(row0 + ai * 128 + m * 16) * D + col0 + bj * 128;
;                     const f32x4 r0 = *(const f32x4*)(res + p), r1 = *(const f32x4*)(res + p + NS);
;                     const f32x4 o0 = r0 + gv[0] * acc[ai][bj][m][0], o1 = r1 + gv[1] * acc[ai][bj][m][1];
;                     *(f32x4*)(out + p) = o0; *(f32x4*)(out + p + NS) = o1;
;                     if (has_xn) { ss[ai * 4 + m] += (o0[0] * o0[0] + o0[1] * o0[1]) + (o0[2] * o0[2] + o0[3] * o0[3]) + (o1[0] * o1[0] + o1[1] * o1[1]) + (o1[2] * o1[2] + o1[3] * o1[3]);
;                         *(u32x4*)(xn + (size_t)(grow0 + ai * 128 + m * 16) * D + col0 + bj * 128) = pack8v(o0 * gs[0], o1 * gs[1]); }
.Lp3e_common:
	s_add_u32 s12, s94, s40
	s_addc_u32 s13, s95, 0
	s_add_u32 s16, s12, 0x4000
	s_addc_u32 s17, s13, 0
	s_add_u32 s12, s12, 0x2000
	s_addc_u32 s13, s13, 0
	s_lshl_b32 s41, s82, 8
	s_or_b32 s41, s41, s67
	v_lshl_add_u32 v180, v226, 3, s41
	v_add_u32_e32 v181, s39, v147
	v_lshlrev_b32_e32 v225, 2, v180
	v_lshl_add_u32 v224, v181, 12, v225
	v_add_u32_e32 v182, s38, v147
	v_lshlrev_b32_e32 v183, 1, v180
	v_lshl_add_u32 v240, v182, 11, v183
	v_mov_b32_e32 v241, 0
	v_mov_b32_e32 v243, 0
	v_mov_b32_e32 v252, 0
	v_mov_b32_e32 v253, 0
	v_mov_b32_e32 v254, 0
	v_mov_b32_e32 v255, 0
	v_mov_b32_e32 v248, 0
	v_mov_b32_e32 v249, 0
	global_load_dwordx4 v[148:151], v225, s[12:13] offset:0
	global_load_dwordx4 v[152:155], v225, s[12:13] offset:16
	global_load_dwordx4 v[156:159], v225, s[12:13] offset:512
	global_load_dwordx4 v[160:163], v225, s[12:13] offset:528
	global_load_dwordx4 v[164:167], v225, s[18:19] offset:0
	global_load_dwordx4 v[168:171], v225, s[18:19] offset:16
	global_load_dwordx4 v[172:175], v225, s[18:19] offset:512
	global_load_dwordx4 v[176:179], v225, s[18:19] offset:528
	global_load_dwordx4 v[212:215], v225, s[16:17] offset:0
	global_load_dwordx4 v[216:219], v225, s[16:17] offset:16
	global_load_dwordx4 v[220:223], v225, s[16:17] offset:512
	global_load_dwordx4 v[232:235], v225, s[16:17] offset:528
	global_load_dwordx4 v[180:183], v224, s[8:9] offset:0 nt
	global_load_dwordx4 v[184:187], v224, s[8:9] offset:16 nt
	global_load_dwordx4 v[188:191], v224, s[8:9] offset:512 nt
	global_load_dwordx4 v[192:195], v224, s[8:9] offset:528 nt
	s_add_u32 s14, s8, 0x10000
	s_addc_u32 s15, s9, 0
	global_load_dwordx4 v[196:199], v224, s[14:15] offset:0 nt
	global_load_dwordx4 v[200:203], v224, s[14:15] offset:16 nt
	global_load_dwordx4 v[204:207], v224, s[14:15] offset:512 nt
	global_load_dwordx4 v[208:211], v224, s[14:15] offset:528 nt
	s_waitcnt vmcnt(8)
	v_pk_mul_f32 v[148:149], v[148:149], 0.5 op_sel_hi:[1,0]
	v_pk_mul_f32 v[150:151], v[150:151], 0.5 op_sel_hi:[1,0]
	v_pk_mul_f32 v[152:153], v[152:153], 0.5 op_sel_hi:[1,0]
	v_pk_mul_f32 v[154:155], v[154:155], 0.5 op_sel_hi:[1,0]
	v_pk_mul_f32 v[156:157], v[156:157], 0.5 op_sel_hi:[1,0]
	v_pk_mul_f32 v[158:159], v[158:159], 0.5 op_sel_hi:[1,0]
	v_pk_mul_f32 v[160:161], v[160:161], 0.5 op_sel_hi:[1,0]
	v_pk_mul_f32 v[162:163], v[162:163], 0.5 op_sel_hi:[1,0]
	v_pk_add_f32 v[212:213], v[212:213], 1.0 op_sel_hi:[1,0]
	v_pk_add_f32 v[214:215], v[214:215], 1.0 op_sel_hi:[1,0]
	v_pk_mul_f32 v[164:165], v[164:165], v[212:213]
	v_pk_mul_f32 v[166:167], v[166:167], v[214:215]
	v_pk_add_f32 v[216:217], v[216:217], 1.0 op_sel_hi:[1,0]
	v_pk_add_f32 v[218:219], v[218:219], 1.0 op_sel_hi:[1,0]
	v_pk_mul_f32 v[168:169], v[168:169], v[216:217]
	v_pk_mul_f32 v[170:171], v[170:171], v[218:219]
	v_pk_add_f32 v[220:221], v[220:221], 1.0 op_sel_hi:[1,0]
	v_pk_add_f32 v[222:223], v[222:223], 1.0 op_sel_hi:[1,0]
	v_pk_mul_f32 v[172:173], v[172:173], v[220:221]
	v_pk_mul_f32 v[174:175], v[174:175], v[222:223]
	v_pk_add_f32 v[232:233], v[232:233], 1.0 op_sel_hi:[1,0]
	v_pk_add_f32 v[234:235], v[234:235], 1.0 op_sel_hi:[1,0]
	v_pk_mul_f32 v[176:177], v[176:177], v[232:233]
	v_pk_mul_f32 v[178:179], v[178:179], v[234:235]
	s_add_u32 s14, s8, 0x20000
	s_addc_u32 s15, s9, 0
	global_load_dwordx4 v[212:215], v224, s[14:15] offset:0 nt
	global_load_dwordx4 v[216:219], v224, s[14:15] offset:16 nt
	global_load_dwordx4 v[220:223], v224, s[14:15] offset:512 nt
	global_load_dwordx4 v[232:235], v224, s[14:15] offset:528 nt
	s_waitcnt vmcnt(8)
	v_pk_fma_f32 v[126:127], v[126:127], v[148:149], v[180:181]
	v_pk_fma_f32 v[128:129], v[128:129], v[150:151], v[182:183]
	v_pk_fma_f32 v[122:123], v[122:123], v[152:153], v[184:185]
	v_pk_fma_f32 v[124:125], v[124:125], v[154:155], v[186:187]
	v_pk_fma_f32 v[62:63], v[62:63], v[156:157], v[188:189]
	v_pk_fma_f32 v[64:65], v[64:65], v[158:159], v[190:191]
	v_pk_fma_f32 v[58:59], v[58:59], v[160:161], v[192:193]
	v_pk_fma_f32 v[60:61], v[60:61], v[162:163], v[194:195]
	global_store_dwordx4 v224, v[126:129], s[10:11] offset:0 nt
	global_store_dwordx4 v224, v[122:125], s[10:11] offset:16 nt
	global_store_dwordx4 v224, v[62:65], s[10:11] offset:512 nt
	global_store_dwordx4 v224, v[58:61], s[10:11] offset:528 nt
	v_fmac_f32_e32 v241, v126, v126
	v_fmac_f32_e32 v241, v127, v127
	v_fmac_f32_e32 v241, v128, v128
	v_fmac_f32_e32 v241, v129, v129
	v_pk_mul_f32 v[180:181], v[126:127], v[164:165]
	v_pk_mul_f32 v[182:183], v[128:129], v[166:167]
	v_fmac_f32_e32 v241, v122, v122
	v_fmac_f32_e32 v241, v123, v123
	v_fmac_f32_e32 v241, v124, v124
	v_fmac_f32_e32 v241, v125, v125
	v_pk_mul_f32 v[184:185], v[122:123], v[168:169]
	v_pk_mul_f32 v[186:187], v[124:125], v[170:171]
	v_cvt_pk_bf16_f32 v180, v180, v181
	v_cvt_pk_bf16_f32 v181, v182, v183
	v_cvt_pk_bf16_f32 v182, v184, v185
	v_cvt_pk_bf16_f32 v183, v186, v187
	global_store_dwordx4 v240, v[180:183], s[60:61] offset:0
	v_fmac_f32_e32 v241, v62, v62
	v_fmac_f32_e32 v241, v63, v63
	v_fmac_f32_e32 v241, v64, v64
	v_fmac_f32_e32 v241, v65, v65
	v_pk_mul_f32 v[188:189], v[62:63], v[172:173]
	v_pk_mul_f32 v[190:191], v[64:65], v[174:175]
	v_fmac_f32_e32 v241, v58, v58
	v_fmac_f32_e32 v241, v59, v59
	v_fmac_f32_e32 v241, v60, v60
	v_fmac_f32_e32 v241, v61, v61
	v_pk_mul_f32 v[192:193], v[58:59], v[176:177]
	v_pk_mul_f32 v[194:195], v[60:61], v[178:179]
	v_cvt_pk_bf16_f32 v188, v188, v189
	v_cvt_pk_bf16_f32 v189, v190, v191
	v_cvt_pk_bf16_f32 v190, v192, v193
	v_cvt_pk_bf16_f32 v191, v194, v195
	global_store_dwordx4 v240, v[188:191], s[60:61] offset:256
	s_nop 0
	s_add_u32 s14, s8, 0x30000
	s_addc_u32 s15, s9, 0
	global_load_dwordx4 v[180:183], v224, s[14:15] offset:0 nt
	global_load_dwordx4 v[184:187], v224, s[14:15] offset:16 nt
	global_load_dwordx4 v[188:191], v224, s[14:15] offset:512 nt
	global_load_dwordx4 v[192:195], v224, s[14:15] offset:528 nt
	s_waitcnt vmcnt(14)
; DEV u32x4 pack8v(const f32x4 a, const f32x4 b) { u32x4 w; w.x = cvt_pk_bf16(a[0], a[1]); w.y = cvt_pk_bf16(a[2], a[3]); w.z = cvt_pk_bf16(b[0], b[1]); w.w = cvt_pk_bf16(b[2], b[3]); return w; }
;     DEV void operator()(const f32x4 (&acc)[2][2][4][2], const Unit& u, int wr, int wc, int fr, int fq) const {
;     ...
;             for (int ai = 0; ai < 2; ++ai)
; #pragma unroll
;                 for (int m = 0; m < 4; ++m) {
;                     const size_t p = (size_t)(row0 + ai * 128 + m * 16) * D + col0 + bj * 128;
;                     const f32x4 r0 = *(const f32x4*)(res + p), r1 = *(const f32x4*)(res + p + NS);
;                     const f32x4 o0 = r0 + gv[0] * acc[ai][bj][m][0], o1 = r1 + gv[1] * acc[ai][bj][m][1];
;                     *(f32x4*)(out + p) = o0; *(f32x4*)(out + p + NS) = o1;
;                     if (has_xn) { ss[ai * 4 + m] += (o0[0] * o0[0] + o0[1] * o0[1]) + (o0[2] * o0[2] + o0[3] * o0[3]) + (o1[0] * o1[0] + o1[1] * o1[1]) + (o1[2] * o1[2] + o1[3] * o1[3]);
;                         *(u32x4*)(xn + (size_t)(grow0 + ai * 128 + m * 16) * D + col0 + bj * 128) = pack8v(o0 * gs[0], o1 * gs[1]); }
	v_pk_fma_f32 v[82:83], v[82:83], v[148:149], v[196:197]
	v_pk_fma_f32 v[84:85], v[84:85], v[150:151], v[198:199]
	v_pk_fma_f32 v[74:75], v[74:75], v[152:153], v[200:201]
	v_pk_fma_f32 v[76:77], v[76:77], v[154:155], v[202:203]
	v_pk_fma_f32 v[54:55], v[54:55], v[156:157], v[204:205]
	v_pk_fma_f32 v[56:57], v[56:57], v[158:159], v[206:207]
	v_pk_fma_f32 v[50:51], v[50:51], v[160:161], v[208:209]
	v_pk_fma_f32 v[52:53], v[52:53], v[162:163], v[210:211]
	s_add_u32 s14, s10, 0x10000
	s_addc_u32 s15, s11, 0
	global_store_dwordx4 v224, v[82:85], s[14:15] offset:0 nt
	global_store_dwordx4 v224, v[74:77], s[14:15] offset:16 nt
	global_store_dwordx4 v224, v[54:57], s[14:15] offset:512 nt
	global_store_dwordx4 v224, v[50:53], s[14:15] offset:528 nt
	s_add_u32 s20, s60, 0x8000
	s_addc_u32 s21, s61, 0
	v_fmac_f32_e32 v243, v82, v82
	v_fmac_f32_e32 v243, v83, v83
	v_fmac_f32_e32 v243, v84, v84
	v_fmac_f32_e32 v243, v85, v85
	v_pk_mul_f32 v[196:197], v[82:83], v[164:165]
	v_pk_mul_f32 v[198:199], v[84:85], v[166:167]
	v_fmac_f32_e32 v243, v74, v74
	v_fmac_f32_e32 v243, v75, v75
	v_fmac_f32_e32 v243, v76, v76
	v_fmac_f32_e32 v243, v77, v77
	v_pk_mul_f32 v[200:201], v[74:75], v[168:169]
	v_pk_mul_f32 v[202:203], v[76:77], v[170:171]
	v_cvt_pk_bf16_f32 v196, v196, v197
	v_cvt_pk_bf16_f32 v197, v198, v199
	v_cvt_pk_bf16_f32 v198, v200, v201
	v_cvt_pk_bf16_f32 v199, v202, v203
	global_store_dwordx4 v240, v[196:199], s[20:21] offset:0
	v_fmac_f32_e32 v243, v54, v54
	v_fmac_f32_e32 v243, v55, v55
	v_fmac_f32_e32 v243, v56, v56
	v_fmac_f32_e32 v243, v57, v57
	v_pk_mul_f32 v[204:205], v[54:55], v[172:173]
	v_pk_mul_f32 v[206:207], v[56:57], v[174:175]
	v_fmac_f32_e32 v243, v50, v50
	v_fmac_f32_e32 v243, v51, v51
	v_fmac_f32_e32 v243, v52, v52
	v_fmac_f32_e32 v243, v53, v53
	v_pk_mul_f32 v[208:209], v[50:51], v[176:177]
	v_pk_mul_f32 v[210:211], v[52:53], v[178:179]
	v_cvt_pk_bf16_f32 v204, v204, v205
	v_cvt_pk_bf16_f32 v205, v206, v207
	v_cvt_pk_bf16_f32 v206, v208, v209
	v_cvt_pk_bf16_f32 v207, v210, v211
	global_store_dwordx4 v240, v[204:207], s[20:21] offset:256
	s_nop 0
	s_add_u32 s14, s8, 0x80000
	s_addc_u32 s15, s9, 0
	global_load_dwordx4 v[196:199], v224, s[14:15] offset:0 nt
	global_load_dwordx4 v[200:203], v224, s[14:15] offset:16 nt
	global_load_dwordx4 v[204:207], v224, s[14:15] offset:512 nt
	global_load_dwordx4 v[208:211], v224, s[14:15] offset:528 nt
	s_waitcnt vmcnt(20)
	v_pk_fma_f32 v[94:95], v[94:95], v[148:149], v[212:213]
	v_pk_fma_f32 v[96:97], v[96:97], v[150:151], v[214:215]
	v_pk_fma_f32 v[90:91], v[90:91], v[152:153], v[216:217]
	v_pk_fma_f32 v[92:93], v[92:93], v[154:155], v[218:219]
	v_pk_fma_f32 v[46:47], v[46:47], v[156:157], v[220:221]
	v_pk_fma_f32 v[48:49], v[48:49], v[158:159], v[222:223]
	v_pk_fma_f32 v[42:43], v[42:43], v[160:161], v[232:233]
	v_pk_fma_f32 v[44:45], v[44:45], v[162:163], v[234:235]
	s_add_u32 s14, s10, 0x20000
	s_addc_u32 s15, s11, 0
	global_store_dwordx4 v224, v[94:97], s[14:15] offset:0 nt
	global_store_dwordx4 v224, v[90:93], s[14:15] offset:16 nt
	global_store_dwordx4 v224, v[46:49], s[14:15] offset:512 nt
	global_store_dwordx4 v224, v[42:45], s[14:15] offset:528 nt
	s_add_u32 s20, s60, 0x10000
	s_addc_u32 s21, s61, 0
	v_fmac_f32_e32 v252, v94, v94
	v_fmac_f32_e32 v252, v95, v95
	v_fmac_f32_e32 v252, v96, v96
	v_fmac_f32_e32 v252, v97, v97
	v_pk_mul_f32 v[212:213], v[94:95], v[164:165]
	v_pk_mul_f32 v[214:215], v[96:97], v[166:167]
	v_fmac_f32_e32 v252, v90, v90
	v_fmac_f32_e32 v252, v91, v91
	v_fmac_f32_e32 v252, v92, v92
	v_fmac_f32_e32 v252, v93, v93
	v_pk_mul_f32 v[216:217], v[90:91], v[168:169]
	v_pk_mul_f32 v[218:219], v[92:93], v[170:171]
	v_cvt_pk_bf16_f32 v212, v212, v213
	v_cvt_pk_bf16_f32 v213, v214, v215
	v_cvt_pk_bf16_f32 v214, v216, v217
	v_cvt_pk_bf16_f32 v215, v218, v219
	global_store_dwordx4 v240, v[212:215], s[20:21] offset:0
	v_fmac_f32_e32 v252, v46, v46
	v_fmac_f32_e32 v252, v47, v47
	v_fmac_f32_e32 v252, v48, v48
	v_fmac_f32_e32 v252, v49, v49
	v_pk_mul_f32 v[220:221], v[46:47], v[172:173]
	v_pk_mul_f32 v[222:223], v[48:49], v[174:175]
	v_fmac_f32_e32 v252, v42, v42
	v_fmac_f32_e32 v252, v43, v43
	v_fmac_f32_e32 v252, v44, v44
	v_fmac_f32_e32 v252, v45, v45
	v_pk_mul_f32 v[232:233], v[42:43], v[176:177]
	v_pk_mul_f32 v[234:235], v[44:45], v[178:179]
	v_cvt_pk_bf16_f32 v220, v220, v221
	v_cvt_pk_bf16_f32 v221, v222, v223
	v_cvt_pk_bf16_f32 v222, v232, v233
	v_cvt_pk_bf16_f32 v223, v234, v235
	global_store_dwordx4 v240, v[220:223], s[20:21] offset:256
	s_nop 0
	s_add_u32 s14, s8, 0x90000
	s_addc_u32 s15, s9, 0
	global_load_dwordx4 v[212:215], v224, s[14:15] offset:0 nt
	global_load_dwordx4 v[216:219], v224, s[14:15] offset:16 nt
	global_load_dwordx4 v[220:223], v224, s[14:15] offset:512 nt
	global_load_dwordx4 v[232:235], v224, s[14:15] offset:528 nt
	s_waitcnt vmcnt(20)
; DEV u32x4 pack8v(const f32x4 a, const f32x4 b) { u32x4 w; w.x = cvt_pk_bf16(a[0], a[1]); w.y = cvt_pk_bf16(a[2], a[3]); w.z = cvt_pk_bf16(b[0], b[1]); w.w = cvt_pk_bf16(b[2], b[3]); return w; }
;     DEV void operator()(const f32x4 (&acc)[2][2][4][2], const Unit& u, int wr, int wc, int fr, int fq) const {
;     ...
;             for (int ai = 0; ai < 2; ++ai)
; #pragma unroll
;                 for (int m = 0; m < 4; ++m) {
;                     const size_t p = (size_t)(row0 + ai * 128 + m * 16) * D + col0 + bj * 128;
;                     const f32x4 r0 = *(const f32x4*)(res + p), r1 = *(const f32x4*)(res + p + NS);
;                     const f32x4 o0 = r0 + gv[0] * acc[ai][bj][m][0], o1 = r1 + gv[1] * acc[ai][bj][m][1];
;                     *(f32x4*)(out + p) = o0; *(f32x4*)(out + p + NS) = o1;
;                     if (has_xn) { ss[ai * 4 + m] += (o0[0] * o0[0] + o0[1] * o0[1]) + (o0[2] * o0[2] + o0[3] * o0[3]) + (o1[0] * o1[0] + o1[1] * o1[1]) + (o1[2] * o1[2] + o1[3] * o1[3]);
;                         *(u32x4*)(xn + (size_t)(grow0 + ai * 128 + m * 16) * D + col0 + bj * 128) = pack8v(o0 * gs[0], o1 * gs[1]); }
	v_pk_fma_f32 v[110:111], v[110:111], v[148:149], v[180:181]
	v_pk_fma_f32 v[112:113], v[112:113], v[150:151], v[182:183]
	v_pk_fma_f32 v[106:107], v[106:107], v[152:153], v[184:185]
	v_pk_fma_f32 v[108:109], v[108:109], v[154:155], v[186:187]
	v_pk_fma_f32 v[38:39], v[38:39], v[156:157], v[188:189]
	v_pk_fma_f32 v[40:41], v[40:41], v[158:159], v[190:191]
	v_pk_fma_f32 v[34:35], v[34:35], v[160:161], v[192:193]
	v_pk_fma_f32 v[36:37], v[36:37], v[162:163], v[194:195]
	s_add_u32 s14, s10, 0x30000
	s_addc_u32 s15, s11, 0
	global_store_dwordx4 v224, v[110:113], s[14:15] offset:0 nt
	global_store_dwordx4 v224, v[106:109], s[14:15] offset:16 nt
	global_store_dwordx4 v224, v[38:41], s[14:15] offset:512 nt
	global_store_dwordx4 v224, v[34:37], s[14:15] offset:528 nt
	s_add_u32 s20, s60, 0x18000
	s_addc_u32 s21, s61, 0
	v_fmac_f32_e32 v253, v110, v110
	v_fmac_f32_e32 v253, v111, v111
	v_fmac_f32_e32 v253, v112, v112
	v_fmac_f32_e32 v253, v113, v113
	v_pk_mul_f32 v[180:181], v[110:111], v[164:165]
	v_pk_mul_f32 v[182:183], v[112:113], v[166:167]
	v_fmac_f32_e32 v253, v106, v106
	v_fmac_f32_e32 v253, v107, v107
	v_fmac_f32_e32 v253, v108, v108
	v_fmac_f32_e32 v253, v109, v109
	v_pk_mul_f32 v[184:185], v[106:107], v[168:169]
	v_pk_mul_f32 v[186:187], v[108:109], v[170:171]
	v_cvt_pk_bf16_f32 v180, v180, v181
	v_cvt_pk_bf16_f32 v181, v182, v183
	v_cvt_pk_bf16_f32 v182, v184, v185
	v_cvt_pk_bf16_f32 v183, v186, v187
	global_store_dwordx4 v240, v[180:183], s[20:21] offset:0
	v_fmac_f32_e32 v253, v38, v38
	v_fmac_f32_e32 v253, v39, v39
	v_fmac_f32_e32 v253, v40, v40
	v_fmac_f32_e32 v253, v41, v41
	v_pk_mul_f32 v[188:189], v[38:39], v[172:173]
	v_pk_mul_f32 v[190:191], v[40:41], v[174:175]
	v_fmac_f32_e32 v253, v34, v34
	v_fmac_f32_e32 v253, v35, v35
	v_fmac_f32_e32 v253, v36, v36
	v_fmac_f32_e32 v253, v37, v37
	v_pk_mul_f32 v[192:193], v[34:35], v[176:177]
	v_pk_mul_f32 v[194:195], v[36:37], v[178:179]
	v_cvt_pk_bf16_f32 v188, v188, v189
	v_cvt_pk_bf16_f32 v189, v190, v191
	v_cvt_pk_bf16_f32 v190, v192, v193
	v_cvt_pk_bf16_f32 v191, v194, v195
	global_store_dwordx4 v240, v[188:191], s[20:21] offset:256
	s_nop 0
	s_add_u32 s14, s8, 0xa0000
	s_addc_u32 s15, s9, 0
	global_load_dwordx4 v[180:183], v224, s[14:15] offset:0 nt
	global_load_dwordx4 v[184:187], v224, s[14:15] offset:16 nt
	global_load_dwordx4 v[188:191], v224, s[14:15] offset:512 nt
	global_load_dwordx4 v[192:195], v224, s[14:15] offset:528 nt
	s_waitcnt vmcnt(20)
	v_pk_fma_f32 v[118:119], v[118:119], v[148:149], v[196:197]
	v_pk_fma_f32 v[120:121], v[120:121], v[150:151], v[198:199]
	v_pk_fma_f32 v[114:115], v[114:115], v[152:153], v[200:201]
	v_pk_fma_f32 v[116:117], v[116:117], v[154:155], v[202:203]
	v_pk_fma_f32 v[30:31], v[30:31], v[156:157], v[204:205]
	v_pk_fma_f32 v[32:33], v[32:33], v[158:159], v[206:207]
	v_pk_fma_f32 v[26:27], v[26:27], v[160:161], v[208:209]
	v_pk_fma_f32 v[28:29], v[28:29], v[162:163], v[210:211]
	s_add_u32 s14, s10, 0x80000
	s_addc_u32 s15, s11, 0
	global_store_dwordx4 v224, v[118:121], s[14:15] offset:0 nt
	global_store_dwordx4 v224, v[114:117], s[14:15] offset:16 nt
	global_store_dwordx4 v224, v[30:33], s[14:15] offset:512 nt
	global_store_dwordx4 v224, v[26:29], s[14:15] offset:528 nt
	s_add_u32 s20, s60, 0x40000
	s_addc_u32 s21, s61, 0
	v_fmac_f32_e32 v254, v118, v118
	v_fmac_f32_e32 v254, v119, v119
	v_fmac_f32_e32 v254, v120, v120
	v_fmac_f32_e32 v254, v121, v121
	v_pk_mul_f32 v[196:197], v[118:119], v[164:165]
	v_pk_mul_f32 v[198:199], v[120:121], v[166:167]
	v_fmac_f32_e32 v254, v114, v114
	v_fmac_f32_e32 v254, v115, v115
	v_fmac_f32_e32 v254, v116, v116
	v_fmac_f32_e32 v254, v117, v117
	v_pk_mul_f32 v[200:201], v[114:115], v[168:169]
	v_pk_mul_f32 v[202:203], v[116:117], v[170:171]
	v_cvt_pk_bf16_f32 v196, v196, v197
	v_cvt_pk_bf16_f32 v197, v198, v199
	v_cvt_pk_bf16_f32 v198, v200, v201
	v_cvt_pk_bf16_f32 v199, v202, v203
	global_store_dwordx4 v240, v[196:199], s[20:21] offset:0
	v_fmac_f32_e32 v254, v30, v30
	v_fmac_f32_e32 v254, v31, v31
	v_fmac_f32_e32 v254, v32, v32
	v_fmac_f32_e32 v254, v33, v33
	v_pk_mul_f32 v[204:205], v[30:31], v[172:173]
	v_pk_mul_f32 v[206:207], v[32:33], v[174:175]
	v_fmac_f32_e32 v254, v26, v26
	v_fmac_f32_e32 v254, v27, v27
	v_fmac_f32_e32 v254, v28, v28
	v_fmac_f32_e32 v254, v29, v29
	v_pk_mul_f32 v[208:209], v[26:27], v[176:177]
	v_pk_mul_f32 v[210:211], v[28:29], v[178:179]
	v_cvt_pk_bf16_f32 v204, v204, v205
	v_cvt_pk_bf16_f32 v205, v206, v207
	v_cvt_pk_bf16_f32 v206, v208, v209
	v_cvt_pk_bf16_f32 v207, v210, v211
	global_store_dwordx4 v240, v[204:207], s[20:21] offset:256
	s_nop 0
	s_add_u32 s14, s8, 0xb0000
	s_addc_u32 s15, s9, 0
	global_load_dwordx4 v[196:199], v224, s[14:15] offset:0 nt
	global_load_dwordx4 v[200:203], v224, s[14:15] offset:16 nt
	global_load_dwordx4 v[204:207], v224, s[14:15] offset:512 nt
	global_load_dwordx4 v[208:211], v224, s[14:15] offset:528 nt
	s_waitcnt vmcnt(20)
; DEV u32x4 pack8v(const f32x4 a, const f32x4 b) { u32x4 w; w.x = cvt_pk_bf16(a[0], a[1]); w.y = cvt_pk_bf16(a[2], a[3]); w.z = cvt_pk_bf16(b[0], b[1]); w.w = cvt_pk_bf16(b[2], b[3]); return w; }
;     DEV void operator()(const f32x4 (&acc)[2][2][4][2], const Unit& u, int wr, int wc, int fr, int fq) const {
;     ...
;             for (int ai = 0; ai < 2; ++ai)
; #pragma unroll
;                 for (int m = 0; m < 4; ++m) {
;                     const size_t p = (size_t)(row0 + ai * 128 + m * 16) * D + col0 + bj * 128;
;                     const f32x4 r0 = *(const f32x4*)(res + p), r1 = *(const f32x4*)(res + p + NS);
;                     const f32x4 o0 = r0 + gv[0] * acc[ai][bj][m][0], o1 = r1 + gv[1] * acc[ai][bj][m][1];
;                     *(f32x4*)(out + p) = o0; *(f32x4*)(out + p + NS) = o1;
;                     if (has_xn) { ss[ai * 4 + m] += (o0[0] * o0[0] + o0[1] * o0[1]) + (o0[2] * o0[2] + o0[3] * o0[3]) + (o1[0] * o1[0] + o1[1] * o1[1]) + (o1[2] * o1[2] + o1[3] * o1[3]);
;                         *(u32x4*)(xn + (size_t)(grow0 + ai * 128 + m * 16) * D + col0 + bj * 128) = pack8v(o0 * gs[0], o1 * gs[1]); }
	v_pk_fma_f32 v[102:103], v[102:103], v[148:149], v[212:213]
	v_pk_fma_f32 v[104:105], v[104:105], v[150:151], v[214:215]
	v_pk_fma_f32 v[98:99], v[98:99], v[152:153], v[216:217]
	v_pk_fma_f32 v[100:101], v[100:101], v[154:155], v[218:219]
	v_pk_fma_f32 v[22:23], v[22:23], v[156:157], v[220:221]
	v_pk_fma_f32 v[24:25], v[24:25], v[158:159], v[222:223]
	v_pk_fma_f32 v[18:19], v[18:19], v[160:161], v[232:233]
	v_pk_fma_f32 v[20:21], v[20:21], v[162:163], v[234:235]
	s_add_u32 s14, s10, 0x90000
	s_addc_u32 s15, s11, 0
	global_store_dwordx4 v224, v[102:105], s[14:15] offset:0 nt
	global_store_dwordx4 v224, v[98:101], s[14:15] offset:16 nt
	global_store_dwordx4 v224, v[22:25], s[14:15] offset:512 nt
	global_store_dwordx4 v224, v[18:21], s[14:15] offset:528 nt
	s_add_u32 s20, s60, 0x48000
	s_addc_u32 s21, s61, 0
	v_fmac_f32_e32 v255, v102, v102
	v_fmac_f32_e32 v255, v103, v103
	v_fmac_f32_e32 v255, v104, v104
	v_fmac_f32_e32 v255, v105, v105
	v_pk_mul_f32 v[212:213], v[102:103], v[164:165]
	v_pk_mul_f32 v[214:215], v[104:105], v[166:167]
	v_fmac_f32_e32 v255, v98, v98
	v_fmac_f32_e32 v255, v99, v99
	v_fmac_f32_e32 v255, v100, v100
	v_fmac_f32_e32 v255, v101, v101
	v_pk_mul_f32 v[216:217], v[98:99], v[168:169]
	v_pk_mul_f32 v[218:219], v[100:101], v[170:171]
	v_cvt_pk_bf16_f32 v212, v212, v213
	v_cvt_pk_bf16_f32 v213, v214, v215
	v_cvt_pk_bf16_f32 v214, v216, v217
	v_cvt_pk_bf16_f32 v215, v218, v219
	global_store_dwordx4 v240, v[212:215], s[20:21] offset:0
	v_fmac_f32_e32 v255, v22, v22
	v_fmac_f32_e32 v255, v23, v23
	v_fmac_f32_e32 v255, v24, v24
	v_fmac_f32_e32 v255, v25, v25
	v_pk_mul_f32 v[220:221], v[22:23], v[172:173]
	v_pk_mul_f32 v[222:223], v[24:25], v[174:175]
	v_fmac_f32_e32 v255, v18, v18
	v_fmac_f32_e32 v255, v19, v19
	v_fmac_f32_e32 v255, v20, v20
	v_fmac_f32_e32 v255, v21, v21
	v_pk_mul_f32 v[232:233], v[18:19], v[176:177]
	v_pk_mul_f32 v[234:235], v[20:21], v[178:179]
	v_cvt_pk_bf16_f32 v220, v220, v221
	v_cvt_pk_bf16_f32 v221, v222, v223
	v_cvt_pk_bf16_f32 v222, v232, v233
	v_cvt_pk_bf16_f32 v223, v234, v235
	global_store_dwordx4 v240, v[220:223], s[20:21] offset:256
	s_nop 0
	s_waitcnt vmcnt(16)
	v_pk_fma_f32 v[86:87], v[86:87], v[148:149], v[180:181]
	v_pk_fma_f32 v[88:89], v[88:89], v[150:151], v[182:183]
	v_pk_fma_f32 v[78:79], v[78:79], v[152:153], v[184:185]
	v_pk_fma_f32 v[80:81], v[80:81], v[154:155], v[186:187]
	v_pk_fma_f32 v[14:15], v[14:15], v[156:157], v[188:189]
	v_pk_fma_f32 v[16:17], v[16:17], v[158:159], v[190:191]
	v_pk_fma_f32 v[10:11], v[10:11], v[160:161], v[192:193]
	v_pk_fma_f32 v[12:13], v[12:13], v[162:163], v[194:195]
	s_add_u32 s14, s10, 0xa0000
	s_addc_u32 s15, s11, 0
	global_store_dwordx4 v224, v[86:89], s[14:15] offset:0 nt
	global_store_dwordx4 v224, v[78:81], s[14:15] offset:16 nt
	global_store_dwordx4 v224, v[14:17], s[14:15] offset:512 nt
	global_store_dwordx4 v224, v[10:13], s[14:15] offset:528 nt
	s_add_u32 s20, s60, 0x50000
	s_addc_u32 s21, s61, 0
	v_fmac_f32_e32 v248, v86, v86
	v_fmac_f32_e32 v248, v87, v87
	v_fmac_f32_e32 v248, v88, v88
	v_fmac_f32_e32 v248, v89, v89
	v_pk_mul_f32 v[180:181], v[86:87], v[164:165]
	v_pk_mul_f32 v[182:183], v[88:89], v[166:167]
	v_fmac_f32_e32 v248, v78, v78
	v_fmac_f32_e32 v248, v79, v79
	v_fmac_f32_e32 v248, v80, v80
	v_fmac_f32_e32 v248, v81, v81
	v_pk_mul_f32 v[184:185], v[78:79], v[168:169]
	v_pk_mul_f32 v[186:187], v[80:81], v[170:171]
	v_cvt_pk_bf16_f32 v180, v180, v181
	v_cvt_pk_bf16_f32 v181, v182, v183
	v_cvt_pk_bf16_f32 v182, v184, v185
	v_cvt_pk_bf16_f32 v183, v186, v187
	global_store_dwordx4 v240, v[180:183], s[20:21] offset:0
	v_fmac_f32_e32 v248, v14, v14
	v_fmac_f32_e32 v248, v15, v15
	v_fmac_f32_e32 v248, v16, v16
	v_fmac_f32_e32 v248, v17, v17
	v_pk_mul_f32 v[188:189], v[14:15], v[172:173]
	v_pk_mul_f32 v[190:191], v[16:17], v[174:175]
	v_fmac_f32_e32 v248, v10, v10
	v_fmac_f32_e32 v248, v11, v11
	v_fmac_f32_e32 v248, v12, v12
	v_fmac_f32_e32 v248, v13, v13
	v_pk_mul_f32 v[192:193], v[10:11], v[176:177]
	v_pk_mul_f32 v[194:195], v[12:13], v[178:179]
	v_cvt_pk_bf16_f32 v188, v188, v189
	v_cvt_pk_bf16_f32 v189, v190, v191
	v_cvt_pk_bf16_f32 v190, v192, v193
	v_cvt_pk_bf16_f32 v191, v194, v195
	global_store_dwordx4 v240, v[188:191], s[20:21] offset:256
	s_nop 0
	s_waitcnt vmcnt(12)
; DEV u32x4 pack8v(const f32x4 a, const f32x4 b) { u32x4 w; w.x = cvt_pk_bf16(a[0], a[1]); w.y = cvt_pk_bf16(a[2], a[3]); w.z = cvt_pk_bf16(b[0], b[1]); w.w = cvt_pk_bf16(b[2], b[3]); return w; }
;     DEV void operator()(const f32x4 (&acc)[2][2][4][2], const Unit& u, int wr, int wc, int fr, int fq) const {
;     ...
;             for (int ai = 0; ai < 2; ++ai)
; #pragma unroll
;                 for (int m = 0; m < 4; ++m) {
;                     const size_t p = (size_t)(row0 + ai * 128 + m * 16) * D + col0 + bj * 128;
;                     const f32x4 r0 = *(const f32x4*)(res + p), r1 = *(const f32x4*)(res + p + NS);
;                     const f32x4 o0 = r0 + gv[0] * acc[ai][bj][m][0], o1 = r1 + gv[1] * acc[ai][bj][m][1];
;                     *(f32x4*)(out + p) = o0; *(f32x4*)(out + p + NS) = o1;
;                     if (has_xn) { ss[ai * 4 + m] += (o0[0] * o0[0] + o0[1] * o0[1]) + (o0[2] * o0[2] + o0[3] * o0[3]) + (o1[0] * o1[0] + o1[1] * o1[1]) + (o1[2] * o1[2] + o1[3] * o1[3]);
;                         *(u32x4*)(xn + (size_t)(grow0 + ai * 128 + m * 16) * D + col0 + bj * 128) = pack8v(o0 * gs[0], o1 * gs[1]); }
;                 }
;         }
;         if (has_xn) {
; #pragma unroll
;             for (int i = 0; i < 8; ++i) { float v = ss[i]; v += __shfl_xor(v, 16); v += __shfl_xor(v, 32); if (fq == 0) rs[(size_t)(grow0 + (i >> 2) * 128 + (i & 3) * 16) * 16 + u.pn * 4 + wc] = v; }
;         }
	v_pk_fma_f32 v[70:71], v[70:71], v[148:149], v[196:197]
	v_pk_fma_f32 v[72:73], v[72:73], v[150:151], v[198:199]
	v_pk_fma_f32 v[66:67], v[66:67], v[152:153], v[200:201]
	v_pk_fma_f32 v[68:69], v[68:69], v[154:155], v[202:203]
	v_pk_fma_f32 v[6:7], v[6:7], v[156:157], v[204:205]
	v_pk_fma_f32 v[8:9], v[8:9], v[158:159], v[206:207]
	v_pk_fma_f32 v[2:3], v[2:3], v[160:161], v[208:209]
	v_pk_fma_f32 v[4:5], v[4:5], v[162:163], v[210:211]
	s_add_u32 s14, s10, 0xb0000
	s_addc_u32 s15, s11, 0
	global_store_dwordx4 v224, v[70:73], s[14:15] offset:0 nt
	global_store_dwordx4 v224, v[66:69], s[14:15] offset:16 nt
	global_store_dwordx4 v224, v[6:9], s[14:15] offset:512 nt
	global_store_dwordx4 v224, v[2:5], s[14:15] offset:528 nt
	s_add_u32 s20, s60, 0x58000
	s_addc_u32 s21, s61, 0
	v_fmac_f32_e32 v249, v70, v70
	v_fmac_f32_e32 v249, v71, v71
	v_fmac_f32_e32 v249, v72, v72
	v_fmac_f32_e32 v249, v73, v73
	v_pk_mul_f32 v[196:197], v[70:71], v[164:165]
	v_pk_mul_f32 v[198:199], v[72:73], v[166:167]
	v_fmac_f32_e32 v249, v66, v66
	v_fmac_f32_e32 v249, v67, v67
	v_fmac_f32_e32 v249, v68, v68
	v_fmac_f32_e32 v249, v69, v69
	v_pk_mul_f32 v[200:201], v[66:67], v[168:169]
	v_pk_mul_f32 v[202:203], v[68:69], v[170:171]
	v_cvt_pk_bf16_f32 v196, v196, v197
	v_cvt_pk_bf16_f32 v197, v198, v199
	v_cvt_pk_bf16_f32 v198, v200, v201
	v_cvt_pk_bf16_f32 v199, v202, v203
	global_store_dwordx4 v240, v[196:199], s[20:21] offset:0
	v_fmac_f32_e32 v249, v6, v6
	v_fmac_f32_e32 v249, v7, v7
	v_fmac_f32_e32 v249, v8, v8
	v_fmac_f32_e32 v249, v9, v9
	v_pk_mul_f32 v[204:205], v[6:7], v[172:173]
	v_pk_mul_f32 v[206:207], v[8:9], v[174:175]
	v_fmac_f32_e32 v249, v2, v2
	v_fmac_f32_e32 v249, v3, v3
	v_fmac_f32_e32 v249, v4, v4
	v_fmac_f32_e32 v249, v5, v5
	v_pk_mul_f32 v[208:209], v[2:3], v[176:177]
	v_pk_mul_f32 v[210:211], v[4:5], v[178:179]
	v_cvt_pk_bf16_f32 v204, v204, v205
	v_cvt_pk_bf16_f32 v205, v206, v207
	v_cvt_pk_bf16_f32 v206, v208, v209
	v_cvt_pk_bf16_f32 v207, v210, v211
	global_store_dwordx4 v240, v[204:207], s[20:21] offset:256
	s_nop 0
	s_nop 1
	v_xor_b32_e32 v180, 16, v231
	v_xor_b32_e32 v181, 32, v231
	v_lshlrev_b32_e32 v180, 2, v180
	v_lshlrev_b32_e32 v181, 2, v181
	ds_bpermute_b32 v196, v180, v241
	ds_bpermute_b32 v197, v180, v243
	ds_bpermute_b32 v198, v180, v252
	ds_bpermute_b32 v199, v180, v253
	ds_bpermute_b32 v200, v180, v254
	ds_bpermute_b32 v201, v180, v255
	ds_bpermute_b32 v202, v180, v248
	ds_bpermute_b32 v203, v180, v249
	s_waitcnt lgkmcnt(0)
	v_add_f32_e32 v241, v241, v196
	v_add_f32_e32 v243, v243, v197
	v_add_f32_e32 v252, v252, v198
	v_add_f32_e32 v253, v253, v199
	v_add_f32_e32 v254, v254, v200
	v_add_f32_e32 v255, v255, v201
	v_add_f32_e32 v248, v248, v202
	v_add_f32_e32 v249, v249, v203
	ds_bpermute_b32 v196, v181, v241
	ds_bpermute_b32 v197, v181, v243
	ds_bpermute_b32 v198, v181, v252
	ds_bpermute_b32 v199, v181, v253
	ds_bpermute_b32 v200, v181, v254
	ds_bpermute_b32 v201, v181, v255
	ds_bpermute_b32 v202, v181, v248
	ds_bpermute_b32 v203, v181, v249
	s_waitcnt lgkmcnt(0)
	v_add_f32_e32 v241, v241, v196
	v_add_f32_e32 v243, v243, v197
	v_add_f32_e32 v252, v252, v198
	v_add_f32_e32 v253, v253, v199
	v_add_f32_e32 v254, v254, v200
	v_add_f32_e32 v255, v255, v201
	v_add_f32_e32 v248, v248, v202
	v_add_f32_e32 v249, v249, v203
	v_add_u32_e32 v182, s38, v147
	v_lshlrev_b32_e32 v182, 6, v182
	s_lshl_b32 s41, s82, 4
	s_add_u32 s14, s76, s41
	s_addc_u32 s15, s77, 0
	s_add_u32 s20, s14, 0x2000
	s_addc_u32 s21, s15, 0
	v_cmp_eq_u32_e32 vcc, 0, v226
	s_nop 4
	s_and_saveexec_b64 s[22:23], vcc
	v_lshrrev_b32_e32 v182, 4, v182
	s_add_u32 s14, s88, 0x3c900000
	s_addc_u32 s15, s89, 0
	global_atomic_add_f32 v182, v241, s[14:15] offset:0
	global_atomic_add_f32 v182, v243, s[14:15] offset:64
	global_atomic_add_f32 v182, v252, s[14:15] offset:128
	global_atomic_add_f32 v182, v253, s[14:15] offset:192
	global_atomic_add_f32 v182, v254, s[14:15] offset:512
	global_atomic_add_f32 v182, v255, s[14:15] offset:576
	global_atomic_add_f32 v182, v248, s[14:15] offset:640
	global_atomic_add_f32 v182, v249, s[14:15] offset:704
	s_or_b64 exec, exec, s[22:23]
	s_and_b64 vcc, exec, s[4:5]
	s_mov_b64 s[4:5], -1
	s_cbranch_vccnz .LBB0_371
	s_andn2_b64 vcc, exec, s[62:63]
	s_cbranch_vccnz .LBB0_370
	s_barrier
	s_branch .LBB0_370

; DEV u32x4 pack8v(const f32x4 a, const f32x4 b) { u32x4 w; w.x = cvt_pk_bf16(a[0], a[1]); w.y = cvt_pk_bf16(a[2], a[3]); w.z = cvt_pk_bf16(b[0], b[1]); w.w = cvt_pk_bf16(b[2], b[3]); return w; }
;     DEV void operator()(const f32x4 (&acc)[2][2][4][2], const Unit& u, int wr, int wc, int fr, int fq) const {
;     ...
;         const bool lat = u.pm < MLAT / 256; const int b = lat ? (u.pm >> 4) : 16;
;         const float* res = lat ? res_lat : res_ctx; float* out = lat ? out_lat : out_ctx;
;         const int grow0 = u.pm * 256 + wr * 64 + fr, row0 = (lat ? grow0 : grow0 - MLAT), col0 = u.pn * 256 + wc * 32 + (PERM ? 8 : 4) * fq;
;         float ss[8];
; #pragma unroll
;         for (int i = 0; i < 8; ++i) ss[i] = 0.f;
; #pragma unroll
;         for (int bj = 0; bj < 2; ++bj) {
;             f32x4 gv[2], gs[2];
; #pragma unroll
;             for (int n = 0; n < 2; ++n) { gv[n] = *(const f32x4*)(mod + (size_t)b * NMOD + gate_i * D + col0 + bj * 128 + NS * n) * coef;
;                 if (has_xn) gs[n] = *(const f32x4*)(g + col0 + bj * 128 + 4 * n) * (*(const f32x4*)(mod + (size_t)b * NMOD + scale_i * D + col0 + bj * 128 + 4 * n) + 1.f); }
; #pragma unroll
;             for (int ai = 0; ai < 2; ++ai)
; #pragma unroll
;                 for (int m = 0; m < 4; ++m) {
;                     const size_t p = (size_t)(row0 + ai * 128 + m * 16) * D + col0 + bj * 128;
;                     const f32x4 r0 = *(const f32x4*)(res + p), r1 = *(const f32x4*)(res + p + NS);
;                     const f32x4 o0 = r0 + gv[0] * acc[ai][bj][m][0], o1 = r1 + gv[1] * acc[ai][bj][m][1];
;                     *(f32x4*)(out + p) = o0; *(f32x4*)(out + p + NS) = o1;
;                     if (has_xn) { ss[ai * 4 + m] += (o0[0] * o0[0] + o0[1] * o0[1]) + (o0[2] * o0[2] + o0[3] * o0[3]) + (o1[0] * o1[0] + o1[1] * o1[1]) + (o1[2] * o1[2] + o1[3] * o1[3]);
;                         *(u32x4*)(xn + (size_t)(grow0 + ai * 128 + m * 16) * D + col0 + bj * 128) = pack8v(o0 * gs[0], o1 * gs[1]); }
.LBB0_1799:
	v_readlane_b32 s76, v242, 31
	v_readlane_b32 s77, v242, 32
	s_lshl_b32 s34, s0, 8
	s_add_u32 s34, s34, s48
	s_ashr_i32 s31, s0, 4
	s_mul_i32 s31, s31, 0x9000
	s_mov_b64 s[68:69], s[86:87]
	s_mov_b32 s35, s34
	s_add_u32 s70, s94, s31
	s_addc_u32 s71, s95, 0
	s_add_u32 s74, s70, 0x7000
	s_addc_u32 s75, s71, 0
	s_add_u32 s70, s70, 0x5000
	s_addc_u32 s71, s71, 0
	s_lshl_b32 s1, s30, 8
	s_or_b32 s1, s1, s49
	v_lshl_add_u32 v180, v220, 3, s1
	v_add_u32_e32 v181, s35, v147
	v_lshlrev_b32_e32 v243, 2, v180
	v_lshl_add_u32 v226, v181, 12, v243
	v_add_u32_e32 v182, s34, v147
	v_lshlrev_b32_e32 v183, 1, v180
	v_lshl_add_u32 v252, v182, 11, v183
	v_mov_b32_e32 v253, 0
	v_mov_b32_e32 v254, 0
	v_mov_b32_e32 v255, 0
	v_mov_b32_e32 v248, 0
	v_mov_b32_e32 v249, 0
	v_mov_b32_e32 v250, 0
	v_mov_b32_e32 v251, 0
	v_mov_b32_e32 v244, 0
	global_load_dwordx4 v[130:133], v243, s[70:71] offset:0
	global_load_dwordx4 v[134:137], v243, s[70:71] offset:16
	global_load_dwordx4 v[156:159], v243, s[70:71] offset:512
	global_load_dwordx4 v[160:163], v243, s[70:71] offset:528
	global_load_dwordx4 v[164:167], v243, s[76:77] offset:0
	global_load_dwordx4 v[168:171], v243, s[76:77] offset:16
	global_load_dwordx4 v[172:175], v243, s[76:77] offset:512
	global_load_dwordx4 v[176:179], v243, s[76:77] offset:528
	global_load_dwordx4 v[212:215], v243, s[74:75] offset:0
	global_load_dwordx4 v[216:219], v243, s[74:75] offset:16
	global_load_dwordx4 v[228:231], v243, s[74:75] offset:512
	global_load_dwordx4 v[232:235], v243, s[74:75] offset:528
	global_load_dwordx4 v[180:183], v226, s[68:69] offset:0 nt
	global_load_dwordx4 v[184:187], v226, s[68:69] offset:16 nt
	global_load_dwordx4 v[188:191], v226, s[68:69] offset:512 nt
	global_load_dwordx4 v[192:195], v226, s[68:69] offset:528 nt
	s_add_u32 s72, s68, 0x10000
	s_addc_u32 s73, s69, 0
	global_load_dwordx4 v[196:199], v226, s[72:73] offset:0 nt
	global_load_dwordx4 v[200:203], v226, s[72:73] offset:16 nt
	global_load_dwordx4 v[204:207], v226, s[72:73] offset:512 nt
	global_load_dwordx4 v[208:211], v226, s[72:73] offset:528 nt
	s_waitcnt vmcnt(8)
	v_pk_add_f32 v[212:213], v[212:213], 1.0 op_sel_hi:[1,0]
	v_pk_add_f32 v[214:215], v[214:215], 1.0 op_sel_hi:[1,0]
	v_pk_mul_f32 v[164:165], v[164:165], v[212:213]
	v_pk_mul_f32 v[166:167], v[166:167], v[214:215]
	v_pk_add_f32 v[216:217], v[216:217], 1.0 op_sel_hi:[1,0]
	v_pk_add_f32 v[218:219], v[218:219], 1.0 op_sel_hi:[1,0]
	v_pk_mul_f32 v[168:169], v[168:169], v[216:217]
	v_pk_mul_f32 v[170:171], v[170:171], v[218:219]
	v_pk_add_f32 v[228:229], v[228:229], 1.0 op_sel_hi:[1,0]
	v_pk_add_f32 v[230:231], v[230:231], 1.0 op_sel_hi:[1,0]
	v_pk_mul_f32 v[172:173], v[172:173], v[228:229]
	v_pk_mul_f32 v[174:175], v[174:175], v[230:231]
	v_pk_add_f32 v[232:233], v[232:233], 1.0 op_sel_hi:[1,0]
	v_pk_add_f32 v[234:235], v[234:235], 1.0 op_sel_hi:[1,0]
	v_pk_mul_f32 v[176:177], v[176:177], v[232:233]
	v_pk_mul_f32 v[178:179], v[178:179], v[234:235]
	s_add_u32 s72, s68, 0x20000
	s_addc_u32 s73, s69, 0
	global_load_dwordx4 v[212:215], v226, s[72:73] offset:0 nt
	global_load_dwordx4 v[216:219], v226, s[72:73] offset:16 nt
	global_load_dwordx4 v[228:231], v226, s[72:73] offset:512 nt
	global_load_dwordx4 v[232:235], v226, s[72:73] offset:528 nt
	s_waitcnt vmcnt(8)
	v_pk_fma_f32 v[126:127], v[126:127], v[130:131], v[180:181]
	v_pk_fma_f32 v[128:129], v[128:129], v[132:133], v[182:183]
	v_pk_fma_f32 v[122:123], v[122:123], v[134:135], v[184:185]
	v_pk_fma_f32 v[124:125], v[124:125], v[136:137], v[186:187]
	v_pk_fma_f32 v[66:67], v[66:67], v[156:157], v[188:189]
	v_pk_fma_f32 v[68:69], v[68:69], v[158:159], v[190:191]
	v_pk_fma_f32 v[58:59], v[58:59], v[160:161], v[192:193]
	v_pk_fma_f32 v[60:61], v[60:61], v[162:163], v[194:195]
	global_store_dwordx4 v226, v[126:129], s[68:69] offset:0 nt
	global_store_dwordx4 v226, v[122:125], s[68:69] offset:16 nt
	global_store_dwordx4 v226, v[66:69], s[68:69] offset:512 nt
	global_store_dwordx4 v226, v[58:61], s[68:69] offset:528 nt
	v_fmac_f32_e32 v253, v126, v126
	v_fmac_f32_e32 v253, v127, v127
	v_fmac_f32_e32 v253, v128, v128
	v_fmac_f32_e32 v253, v129, v129
	v_pk_mul_f32 v[180:181], v[126:127], v[164:165]
	v_pk_mul_f32 v[182:183], v[128:129], v[166:167]
	v_fmac_f32_e32 v253, v122, v122
	v_fmac_f32_e32 v253, v123, v123
	v_fmac_f32_e32 v253, v124, v124
	v_fmac_f32_e32 v253, v125, v125
	v_pk_mul_f32 v[184:185], v[122:123], v[168:169]
	v_pk_mul_f32 v[186:187], v[124:125], v[170:171]
	v_cvt_pk_bf16_f32 v180, v180, v181
	v_cvt_pk_bf16_f32 v181, v182, v183
	v_cvt_pk_bf16_f32 v182, v184, v185
	v_cvt_pk_bf16_f32 v183, v186, v187
	global_store_dwordx4 v252, v[180:183], s[60:61] offset:0
	v_fmac_f32_e32 v253, v66, v66
	v_fmac_f32_e32 v253, v67, v67
	v_fmac_f32_e32 v253, v68, v68
	v_fmac_f32_e32 v253, v69, v69
	v_pk_mul_f32 v[188:189], v[66:67], v[172:173]
	v_pk_mul_f32 v[190:191], v[68:69], v[174:175]
	v_fmac_f32_e32 v253, v58, v58
	v_fmac_f32_e32 v253, v59, v59
	v_fmac_f32_e32 v253, v60, v60
	v_fmac_f32_e32 v253, v61, v61
	v_pk_mul_f32 v[192:193], v[58:59], v[176:177]
	v_pk_mul_f32 v[194:195], v[60:61], v[178:179]
	v_cvt_pk_bf16_f32 v188, v188, v189
	v_cvt_pk_bf16_f32 v189, v190, v191
	v_cvt_pk_bf16_f32 v190, v192, v193
	v_cvt_pk_bf16_f32 v191, v194, v195
	global_store_dwordx4 v252, v[188:191], s[60:61] offset:256
	s_nop 0
	s_add_u32 s72, s68, 0x30000
	s_addc_u32 s73, s69, 0
	global_load_dwordx4 v[180:183], v226, s[72:73] offset:0 nt
	global_load_dwordx4 v[184:187], v226, s[72:73] offset:16 nt
	global_load_dwordx4 v[188:191], v226, s[72:73] offset:512 nt
	global_load_dwordx4 v[192:195], v226, s[72:73] offset:528 nt
	s_waitcnt vmcnt(14)
; DEV u32x4 pack8v(const f32x4 a, const f32x4 b) { u32x4 w; w.x = cvt_pk_bf16(a[0], a[1]); w.y = cvt_pk_bf16(a[2], a[3]); w.z = cvt_pk_bf16(b[0], b[1]); w.w = cvt_pk_bf16(b[2], b[3]); return w; }
;     DEV void operator()(const f32x4 (&acc)[2][2][4][2], const Unit& u, int wr, int wc, int fr, int fq) const {
;     ...
;             for (int ai = 0; ai < 2; ++ai)
; #pragma unroll
;                 for (int m = 0; m < 4; ++m) {
;                     const size_t p = (size_t)(row0 + ai * 128 + m * 16) * D + col0 + bj * 128;
;                     const f32x4 r0 = *(const f32x4*)(res + p), r1 = *(const f32x4*)(res + p + NS);
;                     const f32x4 o0 = r0 + gv[0] * acc[ai][bj][m][0], o1 = r1 + gv[1] * acc[ai][bj][m][1];
;                     *(f32x4*)(out + p) = o0; *(f32x4*)(out + p + NS) = o1;
;                     if (has_xn) { ss[ai * 4 + m] += (o0[0] * o0[0] + o0[1] * o0[1]) + (o0[2] * o0[2] + o0[3] * o0[3]) + (o1[0] * o1[0] + o1[1] * o1[1]) + (o1[2] * o1[2] + o1[3] * o1[3]);
;                         *(u32x4*)(xn + (size_t)(grow0 + ai * 128 + m * 16) * D + col0 + bj * 128) = pack8v(o0 * gs[0], o1 * gs[1]); }
	v_pk_fma_f32 v[118:119], v[118:119], v[130:131], v[196:197]
	v_pk_fma_f32 v[120:121], v[120:121], v[132:133], v[198:199]
	v_pk_fma_f32 v[114:115], v[114:115], v[134:135], v[200:201]
	v_pk_fma_f32 v[116:117], v[116:117], v[136:137], v[202:203]
	v_pk_fma_f32 v[54:55], v[54:55], v[156:157], v[204:205]
	v_pk_fma_f32 v[56:57], v[56:57], v[158:159], v[206:207]
	v_pk_fma_f32 v[50:51], v[50:51], v[160:161], v[208:209]
	v_pk_fma_f32 v[52:53], v[52:53], v[162:163], v[210:211]
	s_add_u32 s72, s68, 0x10000
	s_addc_u32 s73, s69, 0
	global_store_dwordx4 v226, v[118:121], s[72:73] offset:0 nt
	global_store_dwordx4 v226, v[114:117], s[72:73] offset:16 nt
	global_store_dwordx4 v226, v[54:57], s[72:73] offset:512 nt
	global_store_dwordx4 v226, v[50:53], s[72:73] offset:528 nt
	s_add_u32 s78, s60, 0x8000
	s_addc_u32 s79, s61, 0
	v_fmac_f32_e32 v254, v118, v118
	v_fmac_f32_e32 v254, v119, v119
	v_fmac_f32_e32 v254, v120, v120
	v_fmac_f32_e32 v254, v121, v121
	v_pk_mul_f32 v[196:197], v[118:119], v[164:165]
	v_pk_mul_f32 v[198:199], v[120:121], v[166:167]
	v_fmac_f32_e32 v254, v114, v114
	v_fmac_f32_e32 v254, v115, v115
	v_fmac_f32_e32 v254, v116, v116
	v_fmac_f32_e32 v254, v117, v117
	v_pk_mul_f32 v[200:201], v[114:115], v[168:169]
	v_pk_mul_f32 v[202:203], v[116:117], v[170:171]
	v_cvt_pk_bf16_f32 v196, v196, v197
	v_cvt_pk_bf16_f32 v197, v198, v199
	v_cvt_pk_bf16_f32 v198, v200, v201
	v_cvt_pk_bf16_f32 v199, v202, v203
	global_store_dwordx4 v252, v[196:199], s[78:79] offset:0
	v_fmac_f32_e32 v254, v54, v54
	v_fmac_f32_e32 v254, v55, v55
	v_fmac_f32_e32 v254, v56, v56
	v_fmac_f32_e32 v254, v57, v57
	v_pk_mul_f32 v[204:205], v[54:55], v[172:173]
	v_pk_mul_f32 v[206:207], v[56:57], v[174:175]
	v_fmac_f32_e32 v254, v50, v50
	v_fmac_f32_e32 v254, v51, v51
	v_fmac_f32_e32 v254, v52, v52
	v_fmac_f32_e32 v254, v53, v53
	v_pk_mul_f32 v[208:209], v[50:51], v[176:177]
	v_pk_mul_f32 v[210:211], v[52:53], v[178:179]
	v_cvt_pk_bf16_f32 v204, v204, v205
	v_cvt_pk_bf16_f32 v205, v206, v207
	v_cvt_pk_bf16_f32 v206, v208, v209
	v_cvt_pk_bf16_f32 v207, v210, v211
	global_store_dwordx4 v252, v[204:207], s[78:79] offset:256
	s_nop 0
	s_add_u32 s72, s68, 0x80000
	s_addc_u32 s73, s69, 0
	global_load_dwordx4 v[196:199], v226, s[72:73] offset:0 nt
	global_load_dwordx4 v[200:203], v226, s[72:73] offset:16 nt
	global_load_dwordx4 v[204:207], v226, s[72:73] offset:512 nt
	global_load_dwordx4 v[208:211], v226, s[72:73] offset:528 nt
	s_waitcnt vmcnt(20)
	v_pk_fma_f32 v[110:111], v[110:111], v[130:131], v[212:213]
	v_pk_fma_f32 v[112:113], v[112:113], v[132:133], v[214:215]
	v_pk_fma_f32 v[106:107], v[106:107], v[134:135], v[216:217]
	v_pk_fma_f32 v[108:109], v[108:109], v[136:137], v[218:219]
	v_pk_fma_f32 v[46:47], v[46:47], v[156:157], v[228:229]
	v_pk_fma_f32 v[48:49], v[48:49], v[158:159], v[230:231]
	v_pk_fma_f32 v[42:43], v[42:43], v[160:161], v[232:233]
	v_pk_fma_f32 v[44:45], v[44:45], v[162:163], v[234:235]
	s_add_u32 s72, s68, 0x20000
	s_addc_u32 s73, s69, 0
	global_store_dwordx4 v226, v[110:113], s[72:73] offset:0 nt
	global_store_dwordx4 v226, v[106:109], s[72:73] offset:16 nt
	global_store_dwordx4 v226, v[46:49], s[72:73] offset:512 nt
	global_store_dwordx4 v226, v[42:45], s[72:73] offset:528 nt
	s_add_u32 s78, s60, 0x10000
	s_addc_u32 s79, s61, 0
	v_fmac_f32_e32 v255, v110, v110
	v_fmac_f32_e32 v255, v111, v111
	v_fmac_f32_e32 v255, v112, v112
	v_fmac_f32_e32 v255, v113, v113
	v_pk_mul_f32 v[212:213], v[110:111], v[164:165]
	v_pk_mul_f32 v[214:215], v[112:113], v[166:167]
	v_fmac_f32_e32 v255, v106, v106
	v_fmac_f32_e32 v255, v107, v107
	v_fmac_f32_e32 v255, v108, v108
	v_fmac_f32_e32 v255, v109, v109
	v_pk_mul_f32 v[216:217], v[106:107], v[168:169]
	v_pk_mul_f32 v[218:219], v[108:109], v[170:171]
	v_cvt_pk_bf16_f32 v212, v212, v213
	v_cvt_pk_bf16_f32 v213, v214, v215
	v_cvt_pk_bf16_f32 v214, v216, v217
	v_cvt_pk_bf16_f32 v215, v218, v219
	global_store_dwordx4 v252, v[212:215], s[78:79] offset:0
	v_fmac_f32_e32 v255, v46, v46
	v_fmac_f32_e32 v255, v47, v47
	v_fmac_f32_e32 v255, v48, v48
	v_fmac_f32_e32 v255, v49, v49
	v_pk_mul_f32 v[228:229], v[46:47], v[172:173]
	v_pk_mul_f32 v[230:231], v[48:49], v[174:175]
	v_fmac_f32_e32 v255, v42, v42
	v_fmac_f32_e32 v255, v43, v43
	v_fmac_f32_e32 v255, v44, v44
	v_fmac_f32_e32 v255, v45, v45
	v_pk_mul_f32 v[232:233], v[42:43], v[176:177]
	v_pk_mul_f32 v[234:235], v[44:45], v[178:179]
	v_cvt_pk_bf16_f32 v228, v228, v229
	v_cvt_pk_bf16_f32 v229, v230, v231
	v_cvt_pk_bf16_f32 v230, v232, v233
	v_cvt_pk_bf16_f32 v231, v234, v235
	global_store_dwordx4 v252, v[228:231], s[78:79] offset:256
	s_nop 0
	s_add_u32 s72, s68, 0x90000
	s_addc_u32 s73, s69, 0
	global_load_dwordx4 v[212:215], v226, s[72:73] offset:0 nt
	global_load_dwordx4 v[216:219], v226, s[72:73] offset:16 nt
	global_load_dwordx4 v[228:231], v226, s[72:73] offset:512 nt
	global_load_dwordx4 v[232:235], v226, s[72:73] offset:528 nt
	s_waitcnt vmcnt(20)
; DEV u32x4 pack8v(const f32x4 a, const f32x4 b) { u32x4 w; w.x = cvt_pk_bf16(a[0], a[1]); w.y = cvt_pk_bf16(a[2], a[3]); w.z = cvt_pk_bf16(b[0], b[1]); w.w = cvt_pk_bf16(b[2], b[3]); return w; }
;     DEV void operator()(const f32x4 (&acc)[2][2][4][2], const Unit& u, int wr, int wc, int fr, int fq) const {
;     ...
;             for (int ai = 0; ai < 2; ++ai)
; #pragma unroll
;                 for (int m = 0; m < 4; ++m) {
;                     const size_t p = (size_t)(row0 + ai * 128 + m * 16) * D + col0 + bj * 128;
;                     const f32x4 r0 = *(const f32x4*)(res + p), r1 = *(const f32x4*)(res + p + NS);
;                     const f32x4 o0 = r0 + gv[0] * acc[ai][bj][m][0], o1 = r1 + gv[1] * acc[ai][bj][m][1];
;                     *(f32x4*)(out + p) = o0; *(f32x4*)(out + p + NS) = o1;
;                     if (has_xn) { ss[ai * 4 + m] += (o0[0] * o0[0] + o0[1] * o0[1]) + (o0[2] * o0[2] + o0[3] * o0[3]) + (o1[0] * o1[0] + o1[1] * o1[1]) + (o1[2] * o1[2] + o1[3] * o1[3]);
;                         *(u32x4*)(xn + (size_t)(grow0 + ai * 128 + m * 16) * D + col0 + bj * 128) = pack8v(o0 * gs[0], o1 * gs[1]); }
	v_pk_fma_f32 v[102:103], v[102:103], v[130:131], v[180:181]
	v_pk_fma_f32 v[104:105], v[104:105], v[132:133], v[182:183]
	v_pk_fma_f32 v[98:99], v[98:99], v[134:135], v[184:185]
	v_pk_fma_f32 v[100:101], v[100:101], v[136:137], v[186:187]
	v_pk_fma_f32 v[38:39], v[38:39], v[156:157], v[188:189]
	v_pk_fma_f32 v[40:41], v[40:41], v[158:159], v[190:191]
	v_pk_fma_f32 v[34:35], v[34:35], v[160:161], v[192:193]
	v_pk_fma_f32 v[36:37], v[36:37], v[162:163], v[194:195]
	s_add_u32 s72, s68, 0x30000
	s_addc_u32 s73, s69, 0
	global_store_dwordx4 v226, v[102:105], s[72:73] offset:0 nt
	global_store_dwordx4 v226, v[98:101], s[72:73] offset:16 nt
	global_store_dwordx4 v226, v[38:41], s[72:73] offset:512 nt
	global_store_dwordx4 v226, v[34:37], s[72:73] offset:528 nt
	s_add_u32 s78, s60, 0x18000
	s_addc_u32 s79, s61, 0
	v_fmac_f32_e32 v248, v102, v102
	v_fmac_f32_e32 v248, v103, v103
	v_fmac_f32_e32 v248, v104, v104
	v_fmac_f32_e32 v248, v105, v105
	v_pk_mul_f32 v[180:181], v[102:103], v[164:165]
	v_pk_mul_f32 v[182:183], v[104:105], v[166:167]
	v_fmac_f32_e32 v248, v98, v98
	v_fmac_f32_e32 v248, v99, v99
	v_fmac_f32_e32 v248, v100, v100
	v_fmac_f32_e32 v248, v101, v101
	v_pk_mul_f32 v[184:185], v[98:99], v[168:169]
	v_pk_mul_f32 v[186:187], v[100:101], v[170:171]
	v_cvt_pk_bf16_f32 v180, v180, v181
	v_cvt_pk_bf16_f32 v181, v182, v183
	v_cvt_pk_bf16_f32 v182, v184, v185
	v_cvt_pk_bf16_f32 v183, v186, v187
	global_store_dwordx4 v252, v[180:183], s[78:79] offset:0
	v_fmac_f32_e32 v248, v38, v38
	v_fmac_f32_e32 v248, v39, v39
	v_fmac_f32_e32 v248, v40, v40
	v_fmac_f32_e32 v248, v41, v41
	v_pk_mul_f32 v[188:189], v[38:39], v[172:173]
	v_pk_mul_f32 v[190:191], v[40:41], v[174:175]
	v_fmac_f32_e32 v248, v34, v34
	v_fmac_f32_e32 v248, v35, v35
	v_fmac_f32_e32 v248, v36, v36
	v_fmac_f32_e32 v248, v37, v37
	v_pk_mul_f32 v[192:193], v[34:35], v[176:177]
	v_pk_mul_f32 v[194:195], v[36:37], v[178:179]
	v_cvt_pk_bf16_f32 v188, v188, v189
	v_cvt_pk_bf16_f32 v189, v190, v191
	v_cvt_pk_bf16_f32 v190, v192, v193
	v_cvt_pk_bf16_f32 v191, v194, v195
	global_store_dwordx4 v252, v[188:191], s[78:79] offset:256
	s_nop 0
	s_add_u32 s72, s68, 0xa0000
	s_addc_u32 s73, s69, 0
	global_load_dwordx4 v[180:183], v226, s[72:73] offset:0 nt
	global_load_dwordx4 v[184:187], v226, s[72:73] offset:16 nt
	global_load_dwordx4 v[188:191], v226, s[72:73] offset:512 nt
	global_load_dwordx4 v[192:195], v226, s[72:73] offset:528 nt
	s_waitcnt vmcnt(20)
	v_pk_fma_f32 v[94:95], v[94:95], v[130:131], v[196:197]
	v_pk_fma_f32 v[96:97], v[96:97], v[132:133], v[198:199]
	v_pk_fma_f32 v[90:91], v[90:91], v[134:135], v[200:201]
	v_pk_fma_f32 v[92:93], v[92:93], v[136:137], v[202:203]
	v_pk_fma_f32 v[30:31], v[30:31], v[156:157], v[204:205]
	v_pk_fma_f32 v[32:33], v[32:33], v[158:159], v[206:207]
	v_pk_fma_f32 v[26:27], v[26:27], v[160:161], v[208:209]
	v_pk_fma_f32 v[28:29], v[28:29], v[162:163], v[210:211]
	s_add_u32 s72, s68, 0x80000
	s_addc_u32 s73, s69, 0
	global_store_dwordx4 v226, v[94:97], s[72:73] offset:0 nt
	global_store_dwordx4 v226, v[90:93], s[72:73] offset:16 nt
	global_store_dwordx4 v226, v[30:33], s[72:73] offset:512 nt
	global_store_dwordx4 v226, v[26:29], s[72:73] offset:528 nt
	s_add_u32 s78, s60, 0x40000
	s_addc_u32 s79, s61, 0
	v_fmac_f32_e32 v249, v94, v94
	v_fmac_f32_e32 v249, v95, v95
	v_fmac_f32_e32 v249, v96, v96
	v_fmac_f32_e32 v249, v97, v97
	v_pk_mul_f32 v[196:197], v[94:95], v[164:165]
	v_pk_mul_f32 v[198:199], v[96:97], v[166:167]
	v_fmac_f32_e32 v249, v90, v90
	v_fmac_f32_e32 v249, v91, v91
	v_fmac_f32_e32 v249, v92, v92
	v_fmac_f32_e32 v249, v93, v93
	v_pk_mul_f32 v[200:201], v[90:91], v[168:169]
	v_pk_mul_f32 v[202:203], v[92:93], v[170:171]
	v_cvt_pk_bf16_f32 v196, v196, v197
	v_cvt_pk_bf16_f32 v197, v198, v199
	v_cvt_pk_bf16_f32 v198, v200, v201
	v_cvt_pk_bf16_f32 v199, v202, v203
	global_store_dwordx4 v252, v[196:199], s[78:79] offset:0
	v_fmac_f32_e32 v249, v30, v30
	v_fmac_f32_e32 v249, v31, v31
	v_fmac_f32_e32 v249, v32, v32
	v_fmac_f32_e32 v249, v33, v33
	v_pk_mul_f32 v[204:205], v[30:31], v[172:173]
	v_pk_mul_f32 v[206:207], v[32:33], v[174:175]
	v_fmac_f32_e32 v249, v26, v26
	v_fmac_f32_e32 v249, v27, v27
	v_fmac_f32_e32 v249, v28, v28
	v_fmac_f32_e32 v249, v29, v29
	v_pk_mul_f32 v[208:209], v[26:27], v[176:177]
	v_pk_mul_f32 v[210:211], v[28:29], v[178:179]
	v_cvt_pk_bf16_f32 v204, v204, v205
	v_cvt_pk_bf16_f32 v205, v206, v207
	v_cvt_pk_bf16_f32 v206, v208, v209
	v_cvt_pk_bf16_f32 v207, v210, v211
	global_store_dwordx4 v252, v[204:207], s[78:79] offset:256
	s_nop 0
	s_add_u32 s72, s68, 0xb0000
	s_addc_u32 s73, s69, 0
	global_load_dwordx4 v[196:199], v226, s[72:73] offset:0 nt
	global_load_dwordx4 v[200:203], v226, s[72:73] offset:16 nt
	global_load_dwordx4 v[204:207], v226, s[72:73] offset:512 nt
	global_load_dwordx4 v[208:211], v226, s[72:73] offset:528 nt
	s_waitcnt vmcnt(20)
; DEV u32x4 pack8v(const f32x4 a, const f32x4 b) { u32x4 w; w.x = cvt_pk_bf16(a[0], a[1]); w.y = cvt_pk_bf16(a[2], a[3]); w.z = cvt_pk_bf16(b[0], b[1]); w.w = cvt_pk_bf16(b[2], b[3]); return w; }
;     DEV void operator()(const f32x4 (&acc)[2][2][4][2], const Unit& u, int wr, int wc, int fr, int fq) const {
;     ...
;             for (int ai = 0; ai < 2; ++ai)
; #pragma unroll
;                 for (int m = 0; m < 4; ++m) {
;                     const size_t p = (size_t)(row0 + ai * 128 + m * 16) * D + col0 + bj * 128;
;                     const f32x4 r0 = *(const f32x4*)(res + p), r1 = *(const f32x4*)(res + p + NS);
;                     const f32x4 o0 = r0 + gv[0] * acc[ai][bj][m][0], o1 = r1 + gv[1] * acc[ai][bj][m][1];
;                     *(f32x4*)(out + p) = o0; *(f32x4*)(out + p + NS) = o1;
;                     if (has_xn) { ss[ai * 4 + m] += (o0[0] * o0[0] + o0[1] * o0[1]) + (o0[2] * o0[2] + o0[3] * o0[3]) + (o1[0] * o1[0] + o1[1] * o1[1]) + (o1[2] * o1[2] + o1[3] * o1[3]);
;                         *(u32x4*)(xn + (size_t)(grow0 + ai * 128 + m * 16) * D + col0 + bj * 128) = pack8v(o0 * gs[0], o1 * gs[1]); }
	v_pk_fma_f32 v[86:87], v[86:87], v[130:131], v[212:213]
	v_pk_fma_f32 v[88:89], v[88:89], v[132:133], v[214:215]
	v_pk_fma_f32 v[82:83], v[82:83], v[134:135], v[216:217]
	v_pk_fma_f32 v[84:85], v[84:85], v[136:137], v[218:219]
	v_pk_fma_f32 v[22:23], v[22:23], v[156:157], v[228:229]
	v_pk_fma_f32 v[24:25], v[24:25], v[158:159], v[230:231]
	v_pk_fma_f32 v[18:19], v[18:19], v[160:161], v[232:233]
	v_pk_fma_f32 v[20:21], v[20:21], v[162:163], v[234:235]
	s_add_u32 s72, s68, 0x90000
	s_addc_u32 s73, s69, 0
	global_store_dwordx4 v226, v[86:89], s[72:73] offset:0 nt
	global_store_dwordx4 v226, v[82:85], s[72:73] offset:16 nt
	global_store_dwordx4 v226, v[22:25], s[72:73] offset:512 nt
	global_store_dwordx4 v226, v[18:21], s[72:73] offset:528 nt
	s_add_u32 s78, s60, 0x48000
	s_addc_u32 s79, s61, 0
	v_fmac_f32_e32 v250, v86, v86
	v_fmac_f32_e32 v250, v87, v87
	v_fmac_f32_e32 v250, v88, v88
	v_fmac_f32_e32 v250, v89, v89
	v_pk_mul_f32 v[212:213], v[86:87], v[164:165]
	v_pk_mul_f32 v[214:215], v[88:89], v[166:167]
	v_fmac_f32_e32 v250, v82, v82
	v_fmac_f32_e32 v250, v83, v83
	v_fmac_f32_e32 v250, v84, v84
	v_fmac_f32_e32 v250, v85, v85
	v_pk_mul_f32 v[216:217], v[82:83], v[168:169]
	v_pk_mul_f32 v[218:219], v[84:85], v[170:171]
	v_cvt_pk_bf16_f32 v212, v212, v213
	v_cvt_pk_bf16_f32 v213, v214, v215
	v_cvt_pk_bf16_f32 v214, v216, v217
	v_cvt_pk_bf16_f32 v215, v218, v219
	global_store_dwordx4 v252, v[212:215], s[78:79] offset:0
	v_fmac_f32_e32 v250, v22, v22
	v_fmac_f32_e32 v250, v23, v23
	v_fmac_f32_e32 v250, v24, v24
	v_fmac_f32_e32 v250, v25, v25
	v_pk_mul_f32 v[228:229], v[22:23], v[172:173]
	v_pk_mul_f32 v[230:231], v[24:25], v[174:175]
	v_fmac_f32_e32 v250, v18, v18
	v_fmac_f32_e32 v250, v19, v19
	v_fmac_f32_e32 v250, v20, v20
	v_fmac_f32_e32 v250, v21, v21
	v_pk_mul_f32 v[232:233], v[18:19], v[176:177]
	v_pk_mul_f32 v[234:235], v[20:21], v[178:179]
	v_cvt_pk_bf16_f32 v228, v228, v229
	v_cvt_pk_bf16_f32 v229, v230, v231
	v_cvt_pk_bf16_f32 v230, v232, v233
	v_cvt_pk_bf16_f32 v231, v234, v235
	global_store_dwordx4 v252, v[228:231], s[78:79] offset:256
	s_nop 0
	s_waitcnt vmcnt(16)
	v_pk_fma_f32 v[78:79], v[78:79], v[130:131], v[180:181]
	v_pk_fma_f32 v[80:81], v[80:81], v[132:133], v[182:183]
	v_pk_fma_f32 v[74:75], v[74:75], v[134:135], v[184:185]
	v_pk_fma_f32 v[76:77], v[76:77], v[136:137], v[186:187]
	v_pk_fma_f32 v[14:15], v[14:15], v[156:157], v[188:189]
	v_pk_fma_f32 v[16:17], v[16:17], v[158:159], v[190:191]
	v_pk_fma_f32 v[10:11], v[10:11], v[160:161], v[192:193]
	v_pk_fma_f32 v[12:13], v[12:13], v[162:163], v[194:195]
	s_add_u32 s72, s68, 0xa0000
	s_addc_u32 s73, s69, 0
	global_store_dwordx4 v226, v[78:81], s[72:73] offset:0 nt
	global_store_dwordx4 v226, v[74:77], s[72:73] offset:16 nt
	global_store_dwordx4 v226, v[14:17], s[72:73] offset:512 nt
	global_store_dwordx4 v226, v[10:13], s[72:73] offset:528 nt
	s_add_u32 s78, s60, 0x50000
	s_addc_u32 s79, s61, 0
	v_fmac_f32_e32 v251, v78, v78
	v_fmac_f32_e32 v251, v79, v79
	v_fmac_f32_e32 v251, v80, v80
	v_fmac_f32_e32 v251, v81, v81
	v_pk_mul_f32 v[180:181], v[78:79], v[164:165]
	v_pk_mul_f32 v[182:183], v[80:81], v[166:167]
	v_fmac_f32_e32 v251, v74, v74
	v_fmac_f32_e32 v251, v75, v75
	v_fmac_f32_e32 v251, v76, v76
	v_fmac_f32_e32 v251, v77, v77
	v_pk_mul_f32 v[184:185], v[74:75], v[168:169]
	v_pk_mul_f32 v[186:187], v[76:77], v[170:171]
	v_cvt_pk_bf16_f32 v180, v180, v181
	v_cvt_pk_bf16_f32 v181, v182, v183
	v_cvt_pk_bf16_f32 v182, v184, v185
	v_cvt_pk_bf16_f32 v183, v186, v187
	global_store_dwordx4 v252, v[180:183], s[78:79] offset:0
	v_fmac_f32_e32 v251, v14, v14
	v_fmac_f32_e32 v251, v15, v15
	v_fmac_f32_e32 v251, v16, v16
	v_fmac_f32_e32 v251, v17, v17
	v_pk_mul_f32 v[188:189], v[14:15], v[172:173]
	v_pk_mul_f32 v[190:191], v[16:17], v[174:175]
	v_fmac_f32_e32 v251, v10, v10
	v_fmac_f32_e32 v251, v11, v11
	v_fmac_f32_e32 v251, v12, v12
	v_fmac_f32_e32 v251, v13, v13
	v_pk_mul_f32 v[192:193], v[10:11], v[176:177]
	v_pk_mul_f32 v[194:195], v[12:13], v[178:179]
	v_cvt_pk_bf16_f32 v188, v188, v189
	v_cvt_pk_bf16_f32 v189, v190, v191
	v_cvt_pk_bf16_f32 v190, v192, v193
	v_cvt_pk_bf16_f32 v191, v194, v195
	global_store_dwordx4 v252, v[188:191], s[78:79] offset:256
	s_nop 0
	s_waitcnt vmcnt(12)
; DEV u32x4 pack8v(const f32x4 a, const f32x4 b) { u32x4 w; w.x = cvt_pk_bf16(a[0], a[1]); w.y = cvt_pk_bf16(a[2], a[3]); w.z = cvt_pk_bf16(b[0], b[1]); w.w = cvt_pk_bf16(b[2], b[3]); return w; }
;     DEV void operator()(const f32x4 (&acc)[2][2][4][2], const Unit& u, int wr, int wc, int fr, int fq) const {
;     ...
;                     const size_t p = (size_t)(row0 + ai * 128 + m * 16) * D + col0 + bj * 128;
;                     const f32x4 r0 = *(const f32x4*)(res + p), r1 = *(const f32x4*)(res + p + NS);
;                     const f32x4 o0 = r0 + gv[0] * acc[ai][bj][m][0], o1 = r1 + gv[1] * acc[ai][bj][m][1];
;                     *(f32x4*)(out + p) = o0; *(f32x4*)(out + p + NS) = o1;
;                     if (has_xn) { ss[ai * 4 + m] += (o0[0] * o0[0] + o0[1] * o0[1]) + (o0[2] * o0[2] + o0[3] * o0[3]) + (o1[0] * o1[0] + o1[1] * o1[1]) + (o1[2] * o1[2] + o1[3] * o1[3]);
;                         *(u32x4*)(xn + (size_t)(grow0 + ai * 128 + m * 16) * D + col0 + bj * 128) = pack8v(o0 * gs[0], o1 * gs[1]); }
;                 }
;         }
;         if (has_xn) {
; #pragma unroll
;             for (int i = 0; i < 8; ++i) { float v = ss[i]; v += __shfl_xor(v, 16); v += __shfl_xor(v, 32); if (fq == 0) rs[(size_t)(grow0 + (i >> 2) * 128 + (i & 3) * 16) * 16 + u.pn * 4 + wc] = v; }
	v_pk_fma_f32 v[70:71], v[70:71], v[130:131], v[196:197]
	v_pk_fma_f32 v[72:73], v[72:73], v[132:133], v[198:199]
	v_pk_fma_f32 v[62:63], v[62:63], v[134:135], v[200:201]
	v_pk_fma_f32 v[64:65], v[64:65], v[136:137], v[202:203]
	v_pk_fma_f32 v[6:7], v[6:7], v[156:157], v[204:205]
	v_pk_fma_f32 v[8:9], v[8:9], v[158:159], v[206:207]
	v_pk_fma_f32 v[2:3], v[2:3], v[160:161], v[208:209]
	v_pk_fma_f32 v[4:5], v[4:5], v[162:163], v[210:211]
	s_add_u32 s72, s68, 0xb0000
	s_addc_u32 s73, s69, 0
	global_store_dwordx4 v226, v[70:73], s[72:73] offset:0 nt
	global_store_dwordx4 v226, v[62:65], s[72:73] offset:16 nt
	global_store_dwordx4 v226, v[6:9], s[72:73] offset:512 nt
	global_store_dwordx4 v226, v[2:5], s[72:73] offset:528 nt
	s_add_u32 s78, s60, 0x58000
	s_addc_u32 s79, s61, 0
	v_fmac_f32_e32 v244, v70, v70
	v_fmac_f32_e32 v244, v71, v71
	v_fmac_f32_e32 v244, v72, v72
	v_fmac_f32_e32 v244, v73, v73
	v_pk_mul_f32 v[196:197], v[70:71], v[164:165]
	v_pk_mul_f32 v[198:199], v[72:73], v[166:167]
	v_fmac_f32_e32 v244, v62, v62
	v_fmac_f32_e32 v244, v63, v63
	v_fmac_f32_e32 v244, v64, v64
	v_fmac_f32_e32 v244, v65, v65
	v_pk_mul_f32 v[200:201], v[62:63], v[168:169]
	v_pk_mul_f32 v[202:203], v[64:65], v[170:171]
	v_cvt_pk_bf16_f32 v196, v196, v197
	v_cvt_pk_bf16_f32 v197, v198, v199
	v_cvt_pk_bf16_f32 v198, v200, v201
	v_cvt_pk_bf16_f32 v199, v202, v203
	global_store_dwordx4 v252, v[196:199], s[78:79] offset:0
	v_fmac_f32_e32 v244, v6, v6
	v_fmac_f32_e32 v244, v7, v7
	v_fmac_f32_e32 v244, v8, v8
	v_fmac_f32_e32 v244, v9, v9
	v_pk_mul_f32 v[204:205], v[6:7], v[172:173]
	v_pk_mul_f32 v[206:207], v[8:9], v[174:175]
	v_fmac_f32_e32 v244, v2, v2
	v_fmac_f32_e32 v244, v3, v3
	v_fmac_f32_e32 v244, v4, v4
	v_fmac_f32_e32 v244, v5, v5
	v_pk_mul_f32 v[208:209], v[2:3], v[176:177]
	v_pk_mul_f32 v[210:211], v[4:5], v[178:179]
	v_cvt_pk_bf16_f32 v204, v204, v205
	v_cvt_pk_bf16_f32 v205, v206, v207
	v_cvt_pk_bf16_f32 v206, v208, v209
	v_cvt_pk_bf16_f32 v207, v210, v211
	global_store_dwordx4 v252, v[204:207], s[78:79] offset:256
	s_nop 0
	s_nop 1
	v_xor_b32_e32 v180, 16, v225
	v_xor_b32_e32 v181, 32, v225
	v_lshlrev_b32_e32 v180, 2, v180
	v_lshlrev_b32_e32 v181, 2, v181
	ds_bpermute_b32 v196, v180, v253
	ds_bpermute_b32 v197, v180, v254
	ds_bpermute_b32 v198, v180, v255
	ds_bpermute_b32 v199, v180, v248
	ds_bpermute_b32 v200, v180, v249
	ds_bpermute_b32 v201, v180, v250
	ds_bpermute_b32 v202, v180, v251
	ds_bpermute_b32 v203, v180, v244
	s_waitcnt lgkmcnt(0)
	v_add_f32_e32 v253, v253, v196
	v_add_f32_e32 v254, v254, v197
	v_add_f32_e32 v255, v255, v198
	v_add_f32_e32 v248, v248, v199
	v_add_f32_e32 v249, v249, v200
	v_add_f32_e32 v250, v250, v201
	v_add_f32_e32 v251, v251, v202
	v_add_f32_e32 v244, v244, v203
	ds_bpermute_b32 v196, v181, v253
	ds_bpermute_b32 v197, v181, v254
	ds_bpermute_b32 v198, v181, v255
	ds_bpermute_b32 v199, v181, v248
	ds_bpermute_b32 v200, v181, v249
	ds_bpermute_b32 v201, v181, v250
	ds_bpermute_b32 v202, v181, v251
	ds_bpermute_b32 v203, v181, v244
	s_waitcnt lgkmcnt(0)
	v_add_f32_e32 v253, v253, v196
	v_add_f32_e32 v254, v254, v197
	v_add_f32_e32 v255, v255, v198
	v_add_f32_e32 v248, v248, v199
	v_add_f32_e32 v249, v249, v200
	v_add_f32_e32 v250, v250, v201
	v_add_f32_e32 v251, v251, v202
	v_add_f32_e32 v244, v244, v203
	v_add_u32_e32 v182, s34, v147
	v_lshlrev_b32_e32 v182, 6, v182
	s_lshl_b32 s1, s30, 4
	s_add_u32 s72, s55, s1
	s_addc_u32 s73, s58, 0
	s_add_u32 s78, s72, 0x2000
	s_addc_u32 s79, s73, 0
	v_cmp_eq_u32_e32 vcc, 0, v220
	s_nop 4
	s_and_saveexec_b64 s[80:81], vcc
	v_lshrrev_b32_e32 v182, 4, v182
	s_add_u32 s72, s88, 0x3ce00000
	s_addc_u32 s73, s89, 0
	global_atomic_add_f32 v182, v253, s[72:73] offset:0
	global_atomic_add_f32 v182, v254, s[72:73] offset:64
	global_atomic_add_f32 v182, v255, s[72:73] offset:128
	global_atomic_add_f32 v182, v248, s[72:73] offset:192
	global_atomic_add_f32 v182, v249, s[72:73] offset:512
	global_atomic_add_f32 v182, v250, s[72:73] offset:576
	global_atomic_add_f32 v182, v251, s[72:73] offset:640
	global_atomic_add_f32 v182, v244, s[72:73] offset:704
	s_or_b64 exec, exec, s[80:81]
	s_andn2_b64 vcc, exec, s[4:5]
	s_mov_b64 s[0:1], -1
	s_cbranch_vccnz .LBB0_1788
	s_andn2_b64 vcc, exec, s[8:9]
	s_cbranch_vccnz .LBB0_1787
	s_barrier
	s_branch .LBB0_1787

;     DEV void operator()(const f32x4 (&acc)[2][2][4][2], const Unit& u, int wr, int wc, int fr, int fq) const {
;     ...
;         const bool lat = u.pm < MLAT / 256; const int b = lat ? (u.pm >> 4) : 16;
;         const float* res = lat ? res_lat : res_ctx; float* out = lat ? out_lat : out_ctx;
;         const int grow0 = u.pm * 256 + wr * 64 + fr, row0 = (lat ? grow0 : grow0 - MLAT), col0 = u.pn * 256 + wc * 32 + (PERM ? 8 : 4) * fq;
;         float ss[8];
; #pragma unroll
;         for (int i = 0; i < 8; ++i) ss[i] = 0.f;
; #pragma unroll
;         for (int bj = 0; bj < 2; ++bj) {
;             f32x4 gv[2], gs[2];
; #pragma unroll
;             for (int n = 0; n < 2; ++n) { gv[n] = *(const f32x4*)(mod + (size_t)b * NMOD + gate_i * D + col0 + bj * 128 + NS * n) * coef;
;                 if (has_xn) gs[n] = *(const f32x4*)(g + col0 + bj * 128 + 4 * n) * (*(const f32x4*)(mod + (size_t)b * NMOD + scale_i * D + col0 + bj * 128 + 4 * n) + 1.f); }
; #pragma unroll
;             for (int ai = 0; ai < 2; ++ai)
; #pragma unroll
;                 for (int m = 0; m < 4; ++m) {
;                     const size_t p = (size_t)(row0 + ai * 128 + m * 16) * D + col0 + bj * 128;
;                     const f32x4 r0 = *(const f32x4*)(res + p), r1 = *(const f32x4*)(res + p + NS);
;                     const f32x4 o0 = r0 + gv[0] * acc[ai][bj][m][0], o1 = r1 + gv[1] * acc[ai][bj][m][1];
;                     *(f32x4*)(out + p) = o0; *(f32x4*)(out + p + NS) = o1;
;                     if (has_xn) { ss[ai * 4 + m] += (o0[0] * o0[0] + o0[1] * o0[1]) + (o0[2] * o0[2] + o0[3] * o0[3]) + (o1[0] * o1[0] + o1[1] * o1[1]) + (o1[2] * o1[2] + o1[3] * o1[3]);
.LBB0_1991:
	s_lshl_b32 s36, s67, 8
	s_add_u32 s36, s36, s48
	s_ashr_i32 s39, s67, 4
	s_mul_i32 s39, s39, 0x9000
	s_mov_b64 s[16:17], s[86:87]
	s_add_u32 s18, s94, s39
	s_addc_u32 s19, s95, 0
	s_add_u32 s18, s18, 0x8000
	s_addc_u32 s19, s19, 0
	s_lshl_b32 s37, s68, 8
	s_or_b32 s37, s37, s49
	v_lshl_add_u32 v166, v156, 2, s37
	v_add_u32_e32 v167, s36, v147
	v_lshlrev_b32_e32 v252, 2, v166
	v_lshl_add_u32 v243, v167, 12, v252
	v_lshlrev_b32_e32 v253, 6, v167
	v_mov_b32_e32 v248, 0
	v_mov_b32_e32 v249, 0
	v_mov_b32_e32 v250, 0
	v_mov_b32_e32 v251, 0
	v_mov_b32_e32 v244, 0
	v_mov_b32_e32 v245, 0
	v_mov_b32_e32 v246, 0
	v_mov_b32_e32 v247, 0
	global_load_dwordx4 v[142:145], v252, s[18:19] offset:0
	global_load_dwordx4 v[148:151], v252, s[18:19] offset:64
	global_load_dwordx4 v[152:155], v252, s[18:19] offset:512
	global_load_dwordx4 v[162:165], v252, s[18:19] offset:576
	global_load_dwordx4 v[166:169], v243, s[16:17] offset:0 nt
	global_load_dwordx4 v[170:173], v243, s[16:17] offset:64 nt
	global_load_dwordx4 v[174:177], v243, s[16:17] offset:512 nt
	global_load_dwordx4 v[178:181], v243, s[16:17] offset:576 nt
	s_add_u32 s20, s16, 0x10000
	s_addc_u32 s21, s17, 0
	global_load_dwordx4 v[182:185], v243, s[20:21] offset:0 nt
	global_load_dwordx4 v[186:189], v243, s[20:21] offset:64 nt
	global_load_dwordx4 v[190:193], v243, s[20:21] offset:512 nt
	global_load_dwordx4 v[194:197], v243, s[20:21] offset:576 nt
	s_add_u32 s20, s16, 0x20000
	s_addc_u32 s21, s17, 0
	global_load_dwordx4 v[198:201], v243, s[20:21] offset:0 nt
	global_load_dwordx4 v[202:205], v243, s[20:21] offset:64 nt
	global_load_dwordx4 v[206:209], v243, s[20:21] offset:512 nt
	global_load_dwordx4 v[210:213], v243, s[20:21] offset:576 nt
	s_waitcnt vmcnt(12)
	v_pk_mul_f32 v[142:143], v[142:143], 0.5 op_sel_hi:[1,0]
	v_pk_mul_f32 v[144:145], v[144:145], 0.5 op_sel_hi:[1,0]
	v_pk_mul_f32 v[148:149], v[148:149], 0.5 op_sel_hi:[1,0]
	v_pk_mul_f32 v[150:151], v[150:151], 0.5 op_sel_hi:[1,0]
	v_pk_mul_f32 v[152:153], v[152:153], 0.5 op_sel_hi:[1,0]
	v_pk_mul_f32 v[154:155], v[154:155], 0.5 op_sel_hi:[1,0]
	v_pk_mul_f32 v[162:163], v[162:163], 0.5 op_sel_hi:[1,0]
	v_pk_mul_f32 v[164:165], v[164:165], 0.5 op_sel_hi:[1,0]
	s_waitcnt vmcnt(8)
	v_pk_fma_f32 v[126:127], v[126:127], v[142:143], v[166:167]
	v_pk_fma_f32 v[128:129], v[128:129], v[144:145], v[168:169]
	v_pk_fma_f32 v[122:123], v[122:123], v[148:149], v[170:171]
	v_pk_fma_f32 v[124:125], v[124:125], v[150:151], v[172:173]
	v_pk_fma_f32 v[70:71], v[70:71], v[152:153], v[174:175]
	v_pk_fma_f32 v[72:73], v[72:73], v[154:155], v[176:177]
	v_pk_fma_f32 v[66:67], v[66:67], v[162:163], v[178:179]
	v_pk_fma_f32 v[68:69], v[68:69], v[164:165], v[180:181]
	s_add_u32 s20, s16, 0x30000
	s_addc_u32 s21, s17, 0
	global_load_dwordx4 v[166:169], v243, s[20:21] offset:0 nt
	global_load_dwordx4 v[170:173], v243, s[20:21] offset:64 nt
	global_load_dwordx4 v[174:177], v243, s[20:21] offset:512 nt
	global_load_dwordx4 v[178:181], v243, s[20:21] offset:576 nt
	v_fmac_f32_e32 v248, v126, v126
	v_fmac_f32_e32 v248, v127, v127
	v_fmac_f32_e32 v248, v128, v128
	v_fmac_f32_e32 v248, v129, v129
	v_fmac_f32_e32 v248, v122, v122
	v_fmac_f32_e32 v248, v123, v123
	v_fmac_f32_e32 v248, v124, v124
	v_fmac_f32_e32 v248, v125, v125
	v_fmac_f32_e32 v248, v70, v70
	v_fmac_f32_e32 v248, v71, v71
	v_fmac_f32_e32 v248, v72, v72
	v_fmac_f32_e32 v248, v73, v73
	v_fmac_f32_e32 v248, v66, v66
	v_fmac_f32_e32 v248, v67, v67
	v_fmac_f32_e32 v248, v68, v68
	v_fmac_f32_e32 v248, v69, v69
	s_waitcnt vmcnt(8)
	v_pk_fma_f32 v[118:119], v[118:119], v[142:143], v[182:183]
	v_pk_fma_f32 v[120:121], v[120:121], v[144:145], v[184:185]
	v_pk_fma_f32 v[114:115], v[114:115], v[148:149], v[186:187]
	v_pk_fma_f32 v[116:117], v[116:117], v[150:151], v[188:189]
	v_pk_fma_f32 v[54:55], v[54:55], v[152:153], v[190:191]
	v_pk_fma_f32 v[56:57], v[56:57], v[154:155], v[192:193]
	v_pk_fma_f32 v[50:51], v[50:51], v[162:163], v[194:195]
	v_pk_fma_f32 v[52:53], v[52:53], v[164:165], v[196:197]
	s_add_u32 s20, s16, 0x80000
	s_addc_u32 s21, s17, 0
	global_load_dwordx4 v[182:185], v243, s[20:21] offset:0 nt
	global_load_dwordx4 v[186:189], v243, s[20:21] offset:64 nt
	global_load_dwordx4 v[190:193], v243, s[20:21] offset:512 nt
	global_load_dwordx4 v[194:197], v243, s[20:21] offset:576 nt
	v_fmac_f32_e32 v249, v118, v118
	v_fmac_f32_e32 v249, v119, v119
	v_fmac_f32_e32 v249, v120, v120
	v_fmac_f32_e32 v249, v121, v121
	v_fmac_f32_e32 v249, v114, v114
	v_fmac_f32_e32 v249, v115, v115
	v_fmac_f32_e32 v249, v116, v116
	v_fmac_f32_e32 v249, v117, v117
	v_fmac_f32_e32 v249, v54, v54
	v_fmac_f32_e32 v249, v55, v55
	v_fmac_f32_e32 v249, v56, v56
	v_fmac_f32_e32 v249, v57, v57
	v_fmac_f32_e32 v249, v50, v50
	v_fmac_f32_e32 v249, v51, v51
	v_fmac_f32_e32 v249, v52, v52
	v_fmac_f32_e32 v249, v53, v53
	s_waitcnt vmcnt(8)
	v_pk_fma_f32 v[110:111], v[110:111], v[142:143], v[198:199]
	v_pk_fma_f32 v[112:113], v[112:113], v[144:145], v[200:201]
	v_pk_fma_f32 v[106:107], v[106:107], v[148:149], v[202:203]
	v_pk_fma_f32 v[108:109], v[108:109], v[150:151], v[204:205]
	v_pk_fma_f32 v[46:47], v[46:47], v[152:153], v[206:207]
	v_pk_fma_f32 v[48:49], v[48:49], v[154:155], v[208:209]
	v_pk_fma_f32 v[42:43], v[42:43], v[162:163], v[210:211]
	v_pk_fma_f32 v[44:45], v[44:45], v[164:165], v[212:213]
	s_add_u32 s20, s16, 0x90000
	s_addc_u32 s21, s17, 0
	global_load_dwordx4 v[198:201], v243, s[20:21] offset:0 nt
	global_load_dwordx4 v[202:205], v243, s[20:21] offset:64 nt
	global_load_dwordx4 v[206:209], v243, s[20:21] offset:512 nt
	global_load_dwordx4 v[210:213], v243, s[20:21] offset:576 nt
	v_fmac_f32_e32 v250, v110, v110
	v_fmac_f32_e32 v250, v111, v111
	v_fmac_f32_e32 v250, v112, v112
	v_fmac_f32_e32 v250, v113, v113
	v_fmac_f32_e32 v250, v106, v106
	v_fmac_f32_e32 v250, v107, v107
	v_fmac_f32_e32 v250, v108, v108
	v_fmac_f32_e32 v250, v109, v109
	v_fmac_f32_e32 v250, v46, v46
	v_fmac_f32_e32 v250, v47, v47
	v_fmac_f32_e32 v250, v48, v48
	v_fmac_f32_e32 v250, v49, v49
	v_fmac_f32_e32 v250, v42, v42
	v_fmac_f32_e32 v250, v43, v43
	v_fmac_f32_e32 v250, v44, v44
	v_fmac_f32_e32 v250, v45, v45
	s_waitcnt vmcnt(8)
;     DEV void operator()(const f32x4 (&acc)[2][2][4][2], const Unit& u, int wr, int wc, int fr, int fq) const {
;     ...
;             for (int ai = 0; ai < 2; ++ai)
; #pragma unroll
;                 for (int m = 0; m < 4; ++m) {
;                     const size_t p = (size_t)(row0 + ai * 128 + m * 16) * D + col0 + bj * 128;
;                     const f32x4 r0 = *(const f32x4*)(res + p), r1 = *(const f32x4*)(res + p + NS);
;                     const f32x4 o0 = r0 + gv[0] * acc[ai][bj][m][0], o1 = r1 + gv[1] * acc[ai][bj][m][1];
;                     *(f32x4*)(out + p) = o0; *(f32x4*)(out + p + NS) = o1;
;                     if (has_xn) { ss[ai * 4 + m] += (o0[0] * o0[0] + o0[1] * o0[1]) + (o0[2] * o0[2] + o0[3] * o0[3]) + (o1[0] * o1[0] + o1[1] * o1[1]) + (o1[2] * o1[2] + o1[3] * o1[3]);
	v_pk_fma_f32 v[102:103], v[102:103], v[142:143], v[166:167]
	v_pk_fma_f32 v[104:105], v[104:105], v[144:145], v[168:169]
	v_pk_fma_f32 v[98:99], v[98:99], v[148:149], v[170:171]
	v_pk_fma_f32 v[100:101], v[100:101], v[150:151], v[172:173]
	v_pk_fma_f32 v[38:39], v[38:39], v[152:153], v[174:175]
	v_pk_fma_f32 v[40:41], v[40:41], v[154:155], v[176:177]
	v_pk_fma_f32 v[34:35], v[34:35], v[162:163], v[178:179]
	v_pk_fma_f32 v[36:37], v[36:37], v[164:165], v[180:181]
	s_add_u32 s20, s16, 0xa0000
	s_addc_u32 s21, s17, 0
	global_load_dwordx4 v[166:169], v243, s[20:21] offset:0 nt
	global_load_dwordx4 v[170:173], v243, s[20:21] offset:64 nt
	global_load_dwordx4 v[174:177], v243, s[20:21] offset:512 nt
	global_load_dwordx4 v[178:181], v243, s[20:21] offset:576 nt
	v_fmac_f32_e32 v251, v102, v102
	v_fmac_f32_e32 v251, v103, v103
	v_fmac_f32_e32 v251, v104, v104
	v_fmac_f32_e32 v251, v105, v105
	v_fmac_f32_e32 v251, v98, v98
	v_fmac_f32_e32 v251, v99, v99
	v_fmac_f32_e32 v251, v100, v100
	v_fmac_f32_e32 v251, v101, v101
	v_fmac_f32_e32 v251, v38, v38
	v_fmac_f32_e32 v251, v39, v39
	v_fmac_f32_e32 v251, v40, v40
	v_fmac_f32_e32 v251, v41, v41
	v_fmac_f32_e32 v251, v34, v34
	v_fmac_f32_e32 v251, v35, v35
	v_fmac_f32_e32 v251, v36, v36
	v_fmac_f32_e32 v251, v37, v37
	s_waitcnt vmcnt(8)
	v_pk_fma_f32 v[94:95], v[94:95], v[142:143], v[182:183]
	v_pk_fma_f32 v[96:97], v[96:97], v[144:145], v[184:185]
	v_pk_fma_f32 v[90:91], v[90:91], v[148:149], v[186:187]
	v_pk_fma_f32 v[92:93], v[92:93], v[150:151], v[188:189]
	v_pk_fma_f32 v[30:31], v[30:31], v[152:153], v[190:191]
	v_pk_fma_f32 v[32:33], v[32:33], v[154:155], v[192:193]
	v_pk_fma_f32 v[26:27], v[26:27], v[162:163], v[194:195]
	v_pk_fma_f32 v[28:29], v[28:29], v[164:165], v[196:197]
	s_add_u32 s20, s16, 0xb0000
	s_addc_u32 s21, s17, 0
	global_load_dwordx4 v[182:185], v243, s[20:21] offset:0 nt
	global_load_dwordx4 v[186:189], v243, s[20:21] offset:64 nt
	global_load_dwordx4 v[190:193], v243, s[20:21] offset:512 nt
	global_load_dwordx4 v[194:197], v243, s[20:21] offset:576 nt
	v_fmac_f32_e32 v244, v94, v94
	v_fmac_f32_e32 v244, v95, v95
	v_fmac_f32_e32 v244, v96, v96
	v_fmac_f32_e32 v244, v97, v97
	v_fmac_f32_e32 v244, v90, v90
	v_fmac_f32_e32 v244, v91, v91
	v_fmac_f32_e32 v244, v92, v92
	v_fmac_f32_e32 v244, v93, v93
	v_fmac_f32_e32 v244, v30, v30
	v_fmac_f32_e32 v244, v31, v31
	v_fmac_f32_e32 v244, v32, v32
	v_fmac_f32_e32 v244, v33, v33
	v_fmac_f32_e32 v244, v26, v26
	v_fmac_f32_e32 v244, v27, v27
	v_fmac_f32_e32 v244, v28, v28
	v_fmac_f32_e32 v244, v29, v29
	s_waitcnt vmcnt(8)
	v_pk_fma_f32 v[86:87], v[86:87], v[142:143], v[198:199]
	v_pk_fma_f32 v[88:89], v[88:89], v[144:145], v[200:201]
	v_pk_fma_f32 v[82:83], v[82:83], v[148:149], v[202:203]
	v_pk_fma_f32 v[84:85], v[84:85], v[150:151], v[204:205]
	v_pk_fma_f32 v[22:23], v[22:23], v[152:153], v[206:207]
	v_pk_fma_f32 v[24:25], v[24:25], v[154:155], v[208:209]
	v_pk_fma_f32 v[18:19], v[18:19], v[162:163], v[210:211]
	v_pk_fma_f32 v[20:21], v[20:21], v[164:165], v[212:213]
	v_fmac_f32_e32 v245, v86, v86
	v_fmac_f32_e32 v245, v87, v87
	v_fmac_f32_e32 v245, v88, v88
	v_fmac_f32_e32 v245, v89, v89
	v_fmac_f32_e32 v245, v82, v82
	v_fmac_f32_e32 v245, v83, v83
	v_fmac_f32_e32 v245, v84, v84
	v_fmac_f32_e32 v245, v85, v85
	v_fmac_f32_e32 v245, v22, v22
	v_fmac_f32_e32 v245, v23, v23
	v_fmac_f32_e32 v245, v24, v24
	v_fmac_f32_e32 v245, v25, v25
	v_fmac_f32_e32 v245, v18, v18
	v_fmac_f32_e32 v245, v19, v19
	v_fmac_f32_e32 v245, v20, v20
	v_fmac_f32_e32 v245, v21, v21
	s_waitcnt vmcnt(4)
; DEV u32x4 pack8v(const f32x4 a, const f32x4 b) { u32x4 w; w.x = cvt_pk_bf16(a[0], a[1]); w.y = cvt_pk_bf16(a[2], a[3]); w.z = cvt_pk_bf16(b[0], b[1]); w.w = cvt_pk_bf16(b[2], b[3]); return w; }
;     DEV void operator()(const f32x4 (&acc)[2][2][4][2], const Unit& u, int wr, int wc, int fr, int fq) const {
;     ...
;                     if (has_xn) { ss[ai * 4 + m] += (o0[0] * o0[0] + o0[1] * o0[1]) + (o0[2] * o0[2] + o0[3] * o0[3]) + (o1[0] * o1[0] + o1[1] * o1[1]) + (o1[2] * o1[2] + o1[3] * o1[3]);
;                         *(u32x4*)(xn + (size_t)(grow0 + ai * 128 + m * 16) * D + col0 + bj * 128) = pack8v(o0 * gs[0], o1 * gs[1]); }
;                 }
;         }
;         if (has_xn) {
; #pragma unroll
;             for (int i = 0; i < 8; ++i) { float v = ss[i]; v += __shfl_xor(v, 16); v += __shfl_xor(v, 32); if (fq == 0) rs[(size_t)(grow0 + (i >> 2) * 128 + (i & 3) * 16) * 16 + u.pn * 4 + wc] = v; }
	v_pk_fma_f32 v[78:79], v[78:79], v[142:143], v[166:167]
	v_pk_fma_f32 v[80:81], v[80:81], v[144:145], v[168:169]
	v_pk_fma_f32 v[74:75], v[74:75], v[148:149], v[170:171]
	v_pk_fma_f32 v[76:77], v[76:77], v[150:151], v[172:173]
	v_pk_fma_f32 v[14:15], v[14:15], v[152:153], v[174:175]
	v_pk_fma_f32 v[16:17], v[16:17], v[154:155], v[176:177]
	v_pk_fma_f32 v[10:11], v[10:11], v[162:163], v[178:179]
	v_pk_fma_f32 v[12:13], v[12:13], v[164:165], v[180:181]
	v_fmac_f32_e32 v246, v78, v78
	v_fmac_f32_e32 v246, v79, v79
	v_fmac_f32_e32 v246, v80, v80
	v_fmac_f32_e32 v246, v81, v81
	v_fmac_f32_e32 v246, v74, v74
	v_fmac_f32_e32 v246, v75, v75
	v_fmac_f32_e32 v246, v76, v76
	v_fmac_f32_e32 v246, v77, v77
	v_fmac_f32_e32 v246, v14, v14
	v_fmac_f32_e32 v246, v15, v15
	v_fmac_f32_e32 v246, v16, v16
	v_fmac_f32_e32 v246, v17, v17
	v_fmac_f32_e32 v246, v10, v10
	v_fmac_f32_e32 v246, v11, v11
	v_fmac_f32_e32 v246, v12, v12
	v_fmac_f32_e32 v246, v13, v13
	s_waitcnt vmcnt(0)
	v_pk_fma_f32 v[62:63], v[62:63], v[142:143], v[182:183]
	v_pk_fma_f32 v[64:65], v[64:65], v[144:145], v[184:185]
	v_pk_fma_f32 v[58:59], v[58:59], v[148:149], v[186:187]
	v_pk_fma_f32 v[60:61], v[60:61], v[150:151], v[188:189]
	v_pk_fma_f32 v[6:7], v[6:7], v[152:153], v[190:191]
	v_pk_fma_f32 v[8:9], v[8:9], v[154:155], v[192:193]
	v_pk_fma_f32 v[2:3], v[2:3], v[162:163], v[194:195]
	v_pk_fma_f32 v[4:5], v[4:5], v[164:165], v[196:197]
	v_fmac_f32_e32 v247, v62, v62
	v_fmac_f32_e32 v247, v63, v63
	v_fmac_f32_e32 v247, v64, v64
	v_fmac_f32_e32 v247, v65, v65
	v_fmac_f32_e32 v247, v58, v58
	v_fmac_f32_e32 v247, v59, v59
	v_fmac_f32_e32 v247, v60, v60
	v_fmac_f32_e32 v247, v61, v61
	v_fmac_f32_e32 v247, v6, v6
	v_fmac_f32_e32 v247, v7, v7
	v_fmac_f32_e32 v247, v8, v8
	v_fmac_f32_e32 v247, v9, v9
	v_fmac_f32_e32 v247, v2, v2
	v_fmac_f32_e32 v247, v3, v3
	v_fmac_f32_e32 v247, v4, v4
	v_fmac_f32_e32 v247, v5, v5
	v_mbcnt_lo_u32_b32 v255, -1, 0
	v_mbcnt_hi_u32_b32 v255, -1, v255
	v_xor_b32_e32 v254, 16, v255
	v_xor_b32_e32 v255, 32, v255
	v_lshlrev_b32_e32 v254, 2, v254
	v_lshlrev_b32_e32 v255, 2, v255
	ds_bpermute_b32 v182, v254, v248
	ds_bpermute_b32 v183, v254, v249
	ds_bpermute_b32 v184, v254, v250
	ds_bpermute_b32 v185, v254, v251
	ds_bpermute_b32 v186, v254, v244
	ds_bpermute_b32 v187, v254, v245
	ds_bpermute_b32 v188, v254, v246
	ds_bpermute_b32 v189, v254, v247
	s_waitcnt lgkmcnt(0)
	v_add_f32_e32 v248, v248, v182
	v_add_f32_e32 v249, v249, v183
	v_add_f32_e32 v250, v250, v184
	v_add_f32_e32 v251, v251, v185
	v_add_f32_e32 v244, v244, v186
	v_add_f32_e32 v245, v245, v187
	v_add_f32_e32 v246, v246, v188
	v_add_f32_e32 v247, v247, v189
	ds_bpermute_b32 v182, v255, v248
	ds_bpermute_b32 v183, v255, v249
	ds_bpermute_b32 v184, v255, v250
	ds_bpermute_b32 v185, v255, v251
	ds_bpermute_b32 v186, v255, v244
	ds_bpermute_b32 v187, v255, v245
	ds_bpermute_b32 v188, v255, v246
	ds_bpermute_b32 v189, v255, v247
	s_waitcnt lgkmcnt(0)
	v_add_f32_e32 v248, v248, v182
	v_add_f32_e32 v249, v249, v183
	v_add_f32_e32 v250, v250, v184
	v_add_f32_e32 v251, v251, v185
	v_add_f32_e32 v244, v244, v186
	v_add_f32_e32 v245, v245, v187
	v_add_f32_e32 v246, v246, v188
	v_add_f32_e32 v247, v247, v189
	s_lshr_b32 s37, s49, 3
	s_lshl_b32 s38, s68, 4
	s_add_u32 s37, s37, s38
	s_add_u32 s24, s88, 0x3ce00000
	s_addc_u32 s25, s89, 0
	s_add_u32 s20, s24, s37
	s_addc_u32 s21, s25, 0
	v_cmp_eq_u32_e32 vcc, 0, v156
	s_nop 4
	s_and_saveexec_b64 s[28:29], vcc
	global_store_dword v253, v248, s[20:21] offset:0 sc0 sc1
	global_store_dword v253, v249, s[20:21] offset:1024 sc0 sc1
	global_store_dword v253, v250, s[20:21] offset:2048 sc0 sc1
	global_store_dword v253, v251, s[20:21] offset:3072 sc0 sc1
	s_add_u32 s20, s20, 0x2000
	s_addc_u32 s21, s21, 0
	global_store_dword v253, v244, s[20:21] offset:0 sc0 sc1
	global_store_dword v253, v245, s[20:21] offset:1024 sc0 sc1
	global_store_dword v253, v246, s[20:21] offset:2048 sc0 sc1
	global_store_dword v253, v247, s[20:21] offset:3072 sc0 sc1
	s_or_b64 exec, exec, s[28:29]
	s_waitcnt vmcnt(0)
	s_barrier
	s_or_b32 s37, s48, s49
	s_cmp_eq_u32 s37, 0
	s_cbranch_scc0 .Lp13f_nopoll
	s_lshl_b32 s37, s67, 6
	s_add_u32 s37, s37, 0x4000
	s_add_u32 s26, s88, s37
	s_addc_u32 s27, s89, 0
	v_mov_b32_e32 v182, 0
	v_mov_b32_e32 v183, 1
	s_mov_b64 s[28:29], exec
	s_mov_b64 exec, 1
	global_atomic_add v182, v183, s[26:27] offset:0
	s_mov_b32 s38, 0
